# hyena per-channel prologue: all global loads issued up front into spare VGPRs, one wait
# speedup vs baseline: 1.0016x; 1.0016x over previous
; #define LAS __attribute__((address_space(3)))
; __device__ __forceinline__ v4u pack8(const float (&f)[8]) { v4u o; o.x = pk2(f[0], f[1]); o.y = pk2(f[2], f[3]); o.z = pk2(f[4], f[5]); o.w = pk2(f[6], f[7]); return o; }
; __device__ __forceinline__ void phase_hyena(int l, LAS unsigned char* lds, int G) {
;     ...
;     for (int c = blockIdx.x; c < 256; c += G) {
;         {
;             const float wx0 = cw[256 + c], wx1 = cw[768 + 256 + c], wx2 = cw[1536 + 256 + c], bx = cbv[256 + c];
;             const float wv0 = cw[512 + c], wv1 = cw[768 + 512 + c], wv2 = cw[1536 + 512 + c], bv = cbv[512 + c];
; #pragma unroll
;             for (int b = 0; b < 8; ++b) { const bf16r* xr = X1T + ((size_t)c * BATCH + b) * SEQ + tid * 8; const bf16r* vr = VT + ((size_t)c * BATCH + b) * SEQ + tid * 8;
;                 float xf[10], vf[10]; { float t8[8]; unpack8(*(const v4u*)xr, t8);
; #pragma unroll
;                     for (int e = 0; e < 8; ++e) xf[e + 1] = t8[e]; unpack8(*(const v4u*)vr, t8);
; #pragma unroll
;                     for (int e = 0; e < 8; ++e) vf[e + 1] = t8[e]; }
;                 xf[0] = tid > 0 ? bf1(xr[-1]) : 0.f; vf[0] = tid > 0 ? bf1(vr[-1]) : 0.f; xf[9] = tid < NTHR - 1 ? bf1(xr[8]) : 0.f; vf[9] = tid < NTHR - 1 ? bf1(vr[8]) : 0.f;
;                 float z[8];
; #pragma unroll
;                 for (int e = 0; e < 8; ++e) z[e] = (wx0 * xf[e] + wx1 * xf[e + 1] + wx2 * xf[e + 2] + bx) * (wv0 * vf[e] + wv1 * vf[e + 1] + wv2 * vf[e + 2] + bv);
;                 *(LAS v4u*)(Zs + b * ZPITCH + tid * 16) = pack8(z); }
;         }
; #pragma unroll
;         for (int i = 0; i < 2; ++i) { *(LAS v4u*)((LAS unsigned char*)rl + (i * NTHR + tid) * 16) = *(const v4u*)(RG + (size_t)c * 8192 + (i * NTHR + tid) * 8);
;             *(LAS v4u*)((LAS unsigned char*)rl + RG1_LDS + (i * NTHR + tid) * 16) = *(const v4u*)(RG1 + (size_t)c * 8192 + (i * NTHR + tid) * 8); }
.LBB0_476:
	s_ashr_i32 s35, s34, 31
	s_lshl_b64 s[46:47], s[34:35], 2
	s_add_u32 s2, s58, s46
	s_addc_u32 s3, s59, s47
	s_add_u32 s14, s60, s46
	s_addc_u32 s15, s61, s47
	global_load_dword v18, v1, s[2:3] offset:1024
	global_load_dword v19, v221, s[2:3]
	global_load_dword v12, v221, s[2:3] offset:3072
	global_load_dword v14, v1, s[14:15] offset:1024
	global_load_dword v10, v1, s[14:15] offset:2048
	global_load_dword v20, v1, s[2:3] offset:2048
	global_load_dword v16, v222, s[2:3]
	global_load_dword v21, v221, s[2:3] offset:1024
	s_lshl_b64 s[44:45], s[34:35], 16
	s_lshl_b64 s[2:3], s[34:35], 14
	s_add_u32 s14, s62, s2
	s_addc_u32 s15, s63, s3
	s_add_u32 s2, s64, s2
	s_addc_u32 s3, s65, s3
	v_lshl_add_u64 v[228:229], s[14:15], 0, v[136:137]
	v_lshl_add_u64 v[230:231], s[2:3], 0, v[136:137]
	v_lshl_add_u64 v[232:233], s[14:15], 0, v[138:139]
	v_lshl_add_u64 v[234:235], s[2:3], 0, v[138:139]
	s_mov_b32 s98, 0x2000
	s_mov_b32 s99, 0
	v_lshl_add_u64 v[236:237], v[124:125], 0, s[44:45]
	v_lshl_add_u64 v[238:239], v[126:127], 0, s[44:45]
	global_load_dwordx4 v[60:63], v[236:237], off
	global_load_dwordx4 v[64:67], v[238:239], off
	s_and_saveexec_b64 s[48:49], s[40:41]
	global_load_ushort v157, v[236:237], off offset:-2
	global_load_ushort v158, v[238:239], off offset:-2
	s_or_b64 exec, exec, s[48:49]
	s_and_saveexec_b64 s[48:49], s[42:43]
	global_load_ushort v159, v[236:237], off offset:16
	global_load_ushort v160, v[238:239], off offset:16
	s_or_b64 exec, exec, s[48:49]
	v_lshl_add_u64 v[236:237], v[236:237], 0, s[98:99]
	v_lshl_add_u64 v[238:239], v[238:239], 0, s[98:99]
	global_load_dwordx4 v[68:71], v[236:237], off
	global_load_dwordx4 v[72:75], v[238:239], off
	s_and_saveexec_b64 s[48:49], s[40:41]
	global_load_ushort v161, v[236:237], off offset:-2
	global_load_ushort v162, v[238:239], off offset:-2
	s_or_b64 exec, exec, s[48:49]
	s_and_saveexec_b64 s[48:49], s[42:43]
	global_load_ushort v163, v[236:237], off offset:16
	global_load_ushort v164, v[238:239], off offset:16
	s_or_b64 exec, exec, s[48:49]
	v_lshl_add_u64 v[236:237], v[236:237], 0, s[98:99]
	v_lshl_add_u64 v[238:239], v[238:239], 0, s[98:99]
	global_load_dwordx4 v[76:79], v[236:237], off
	global_load_dwordx4 v[80:83], v[238:239], off
	s_and_saveexec_b64 s[48:49], s[40:41]
	global_load_ushort v165, v[236:237], off offset:-2
	global_load_ushort v166, v[238:239], off offset:-2
	s_or_b64 exec, exec, s[48:49]
	s_and_saveexec_b64 s[48:49], s[42:43]
	global_load_ushort v167, v[236:237], off offset:16
	global_load_ushort v168, v[238:239], off offset:16
	s_or_b64 exec, exec, s[48:49]
	v_lshl_add_u64 v[236:237], v[236:237], 0, s[98:99]
	v_lshl_add_u64 v[238:239], v[238:239], 0, s[98:99]
	global_load_dwordx4 v[84:87], v[236:237], off
	global_load_dwordx4 v[88:91], v[238:239], off
	s_and_saveexec_b64 s[48:49], s[40:41]
	global_load_ushort v169, v[236:237], off offset:-2
	global_load_ushort v170, v[238:239], off offset:-2
	s_or_b64 exec, exec, s[48:49]
	s_and_saveexec_b64 s[48:49], s[42:43]
	global_load_ushort v171, v[236:237], off offset:16
	global_load_ushort v172, v[238:239], off offset:16
	s_or_b64 exec, exec, s[48:49]
	v_lshl_add_u64 v[236:237], v[236:237], 0, s[98:99]
	v_lshl_add_u64 v[238:239], v[238:239], 0, s[98:99]
	global_load_dwordx4 v[92:95], v[236:237], off
	global_load_dwordx4 v[96:99], v[238:239], off
	s_and_saveexec_b64 s[48:49], s[40:41]
	global_load_ushort v173, v[236:237], off offset:-2
	global_load_ushort v174, v[238:239], off offset:-2
	s_or_b64 exec, exec, s[48:49]
	s_and_saveexec_b64 s[48:49], s[42:43]
	global_load_ushort v175, v[236:237], off offset:16
	global_load_ushort v176, v[238:239], off offset:16
	s_or_b64 exec, exec, s[48:49]
	v_lshl_add_u64 v[236:237], v[236:237], 0, s[98:99]
	v_lshl_add_u64 v[238:239], v[238:239], 0, s[98:99]
	global_load_dwordx4 v[100:103], v[236:237], off
	global_load_dwordx4 v[104:107], v[238:239], off
	s_and_saveexec_b64 s[48:49], s[40:41]
	global_load_ushort v177, v[236:237], off offset:-2
	global_load_ushort v178, v[238:239], off offset:-2
	s_or_b64 exec, exec, s[48:49]
	s_and_saveexec_b64 s[48:49], s[42:43]
	global_load_ushort v179, v[236:237], off offset:16
	global_load_ushort v180, v[238:239], off offset:16
	s_or_b64 exec, exec, s[48:49]
	v_lshl_add_u64 v[236:237], v[236:237], 0, s[98:99]
	v_lshl_add_u64 v[238:239], v[238:239], 0, s[98:99]
	global_load_dwordx4 v[108:111], v[236:237], off
	global_load_dwordx4 v[112:115], v[238:239], off
	s_and_saveexec_b64 s[48:49], s[40:41]
	global_load_ushort v181, v[236:237], off offset:-2
	global_load_ushort v182, v[238:239], off offset:-2
	s_or_b64 exec, exec, s[48:49]
	s_and_saveexec_b64 s[48:49], s[42:43]
	global_load_ushort v183, v[236:237], off offset:16
	global_load_ushort v184, v[238:239], off offset:16
	s_or_b64 exec, exec, s[48:49]
	v_lshl_add_u64 v[236:237], v[236:237], 0, s[98:99]
	v_lshl_add_u64 v[238:239], v[238:239], 0, s[98:99]
	global_load_dwordx4 v[116:119], v[236:237], off
	global_load_dwordx4 v[120:123], v[238:239], off
	s_and_saveexec_b64 s[48:49], s[40:41]
	global_load_ushort v185, v[236:237], off offset:-2
	global_load_ushort v186, v[238:239], off offset:-2
	s_or_b64 exec, exec, s[48:49]
	s_and_saveexec_b64 s[48:49], s[42:43]
	global_load_ushort v187, v[236:237], off offset:16
	global_load_ushort v188, v[238:239], off offset:16
	s_or_b64 exec, exec, s[48:49]
	global_load_dwordx4 v[202:205], v[228:229], off
	global_load_dwordx4 v[206:209], v[230:231], off
	global_load_dwordx4 v[210:213], v[232:233], off
	global_load_dwordx4 v[214:217], v[234:235], off
	s_waitcnt vmcnt(0)
	v_lshl_add_u64 v[28:29], v[124:125], 0, s[44:45]
	v_lshl_add_u64 v[30:31], v[126:127], 0, s[44:45]
	v_mov_b64_e32 v[6:7], v[60:61]
	v_mov_b64_e32 v[8:9], v[62:63]
	v_mov_b64_e32 v[2:3], v[64:65]
	v_mov_b64_e32 v[4:5], v[66:67]
	v_mov_b32_e32 v26, 0
	v_mov_b32_e32 v24, 0
	v_mov_b32_e32 v22, 0
	s_and_saveexec_b64 s[48:49], s[40:41]
	s_cbranch_execz .LBB0_478
	v_mov_b32_e32 v0, v157
	v_mov_b32_e32 v11, v158
	s_waitcnt vmcnt(1)
	v_lshlrev_b32_e32 v24, 16, v0
	s_waitcnt vmcnt(0)
	v_lshlrev_b32_e32 v22, 16, v11
; #define LAS __attribute__((address_space(3)))
; __device__ __forceinline__ v4u pack8(const float (&f)[8]) { v4u o; o.x = pk2(f[0], f[1]); o.y = pk2(f[2], f[3]); o.z = pk2(f[4], f[5]); o.w = pk2(f[6], f[7]); return o; }
; __device__ __forceinline__ void phase_hyena(int l, LAS unsigned char* lds, int G) {
;     ...
;             for (int b = 0; b < 8; ++b) { const bf16r* xr = X1T + ((size_t)c * BATCH + b) * SEQ + tid * 8; const bf16r* vr = VT + ((size_t)c * BATCH + b) * SEQ + tid * 8;
;                 float xf[10], vf[10]; { float t8[8]; unpack8(*(const v4u*)xr, t8);
; #pragma unroll
;                     for (int e = 0; e < 8; ++e) xf[e + 1] = t8[e]; unpack8(*(const v4u*)vr, t8);
; #pragma unroll
;                     for (int e = 0; e < 8; ++e) vf[e + 1] = t8[e]; }
;                 xf[0] = tid > 0 ? bf1(xr[-1]) : 0.f; vf[0] = tid > 0 ? bf1(vr[-1]) : 0.f; xf[9] = tid < NTHR - 1 ? bf1(xr[8]) : 0.f; vf[9] = tid < NTHR - 1 ? bf1(vr[8]) : 0.f;
;                 float z[8];
; #pragma unroll
;                 for (int e = 0; e < 8; ++e) z[e] = (wx0 * xf[e] + wx1 * xf[e + 1] + wx2 * xf[e + 2] + bx) * (wv0 * vf[e] + wv1 * vf[e + 1] + wv2 * vf[e + 2] + bv);
;                 *(LAS v4u*)(Zs + b * ZPITCH + tid * 16) = pack8(z); }
.LBB0_478:
	s_or_b64 exec, exec, s[48:49]
	v_mov_b32_e32 v27, 0
	s_and_saveexec_b64 s[48:49], s[42:43]
	s_cbranch_execz .LBB0_480
	v_mov_b32_e32 v0, v159
	v_mov_b32_e32 v11, v160
	s_waitcnt vmcnt(1)
	v_lshlrev_b32_e32 v26, 16, v0
	s_waitcnt vmcnt(0)
	v_lshlrev_b32_e32 v27, 16, v11
.LBB0_480:
	s_or_b64 exec, exec, s[48:49]
	s_waitcnt vmcnt(1)
	v_and_b32_e32 v29, 0xffff0000, v6
	s_waitcnt vmcnt(0)
	v_and_b32_e32 v39, 0xffff0000, v2
	v_lshlrev_b32_e32 v31, 16, v7
	v_mov_b32_e32 v30, v29
	v_lshlrev_b32_e32 v41, 16, v3
	v_mov_b32_e32 v40, v39
	v_mov_b32_e32 v0, v19
	v_mov_b32_e32 v52, v21
	v_lshlrev_b32_e32 v28, 16, v6
	v_mov_b32_e32 v33, v31
	v_mov_b32_e32 v6, v31
	v_lshlrev_b32_e32 v38, 16, v2
	v_mov_b32_e32 v43, v41
	v_mov_b32_e32 v44, v41
	v_pk_mul_f32 v[30:31], v[0:1], v[30:31] op_sel_hi:[0,1]
	v_pk_mul_f32 v[40:41], v[52:53], v[40:41] op_sel_hi:[0,1]
	v_mov_b32_e32 v32, v28
	v_and_b32_e32 v7, 0xffff0000, v7
	v_mov_b32_e32 v34, v29
	v_and_b32_e32 v45, 0xffff0000, v3
	v_pk_fma_f32 v[28:29], v[18:19], v[28:29], v[30:31] op_sel_hi:[0,1,1]
	v_pk_fma_f32 v[30:31], v[20:21], v[38:39], v[40:41] op_sel_hi:[0,1,1]
	v_mov_b32_e32 v25, v7
	v_mov_b32_e32 v23, v45
	v_pk_fma_f32 v[28:29], v[12:13], v[6:7], v[28:29] op_sel_hi:[0,1,1]
	v_pk_fma_f32 v[30:31], v[16:17], v[44:45], v[30:31] op_sel_hi:[0,1,1]
	v_mov_b32_e32 v42, v38
	v_pk_mul_f32 v[2:3], v[18:19], v[24:25]
	v_mov_b32_e32 v24, v19
	v_mov_b32_e32 v25, v18
	v_pk_mul_f32 v[50:51], v[20:21], v[22:23]
	v_mov_b32_e32 v22, v21
	v_mov_b32_e32 v23, v20
	v_pk_add_f32 v[28:29], v[14:15], v[28:29] op_sel_hi:[0,1]
	v_pk_add_f32 v[30:31], v[10:11], v[30:31] op_sel_hi:[0,1]
	v_lshlrev_b32_e32 v35, 16, v8
	v_lshlrev_b32_e32 v47, 16, v4
	v_mov_b32_e32 v46, v39
	v_pk_mul_f32 v[28:29], v[28:29], v[30:31]
	v_pk_fma_f32 v[2:3], v[24:25], v[32:33], v[2:3]
	v_pk_fma_f32 v[30:31], v[22:23], v[42:43], v[50:51]
	v_pk_fma_f32 v[2:3], v[12:13], v[34:35], v[2:3] op_sel_hi:[0,1,1]
	v_pk_fma_f32 v[30:31], v[16:17], v[46:47], v[30:31] op_sel_hi:[0,1,1]
	v_pk_add_f32 v[2:3], v[14:15], v[2:3] op_sel_hi:[0,1]
	v_pk_add_f32 v[30:31], v[10:11], v[30:31] op_sel_hi:[0,1]
	v_pk_mul_f32 v[2:3], v[2:3], v[30:31]
	v_lshlrev_b32_e32 v37, 16, v9
	v_and_b32_sdwa v13, v3, v220 dst_sel:DWORD dst_unused:UNUSED_PAD src0_sel:WORD_1 src1_sel:DWORD
	v_and_b32_sdwa v6, v29, v220 dst_sel:DWORD dst_unused:UNUSED_PAD src0_sel:WORD_1 src1_sel:DWORD
	v_and_b32_sdwa v11, v28, v220 dst_sel:DWORD dst_unused:UNUSED_PAD src0_sel:WORD_1 src1_sel:DWORD
	v_add3_u32 v3, v3, v13, s72
	v_lshlrev_b32_e32 v49, 16, v5
	v_and_b32_e32 v9, 0xffff0000, v9
	v_and_b32_e32 v8, 0xffff0000, v8
	v_add3_u32 v6, v29, v6, s72
	v_add3_u32 v11, v28, v11, s72
	v_and_b32_e32 v3, 0xffff0000, v3
	v_mov_b32_e32 v28, v35
	v_mov_b32_e32 v29, v37
	v_and_b32_e32 v5, 0xffff0000, v5
	v_and_b32_e32 v4, 0xffff0000, v4
	v_or_b32_sdwa v3, v3, v6 dst_sel:DWORD dst_unused:UNUSED_PAD src0_sel:DWORD src1_sel:WORD_1
	v_pk_mov_b32 v[6:7], v[6:7], v[8:9] op_sel:[1,0]
	v_pk_mul_f32 v[28:29], v[0:1], v[28:29] op_sel_hi:[0,1]
	v_mov_b32_e32 v30, v47
	v_mov_b32_e32 v31, v49
	v_pk_fma_f32 v[6:7], v[18:19], v[6:7], v[28:29] op_sel_hi:[0,1,1]
	v_pk_mov_b32 v[28:29], v[44:45], v[4:5] op_sel:[1,0]
	v_pk_mul_f32 v[30:31], v[52:53], v[30:31] op_sel_hi:[0,1]
	v_pk_fma_f32 v[28:29], v[20:21], v[28:29], v[30:31] op_sel_hi:[0,1,1]
	v_and_b32_e32 v11, 0xffff0000, v11
	v_and_b32_sdwa v15, v2, v220 dst_sel:DWORD dst_unused:UNUSED_PAD src0_sel:WORD_1 src1_sel:DWORD
	v_pk_fma_f32 v[6:7], v[12:13], v[8:9], v[6:7] op_sel_hi:[0,1,1]
	v_pk_fma_f32 v[28:29], v[16:17], v[4:5], v[28:29] op_sel_hi:[0,1,1]
	v_mov_b32_e32 v34, v9
	v_mov_b32_e32 v46, v5
	v_mov_b32_e32 v36, v8
	v_mov_b32_e32 v48, v4
	v_pk_add_f32 v[6:7], v[14:15], v[6:7] op_sel_hi:[0,1]
	v_pk_add_f32 v[28:29], v[10:11], v[28:29] op_sel_hi:[0,1]
	v_pk_mul_f32 v[8:9], v[24:25], v[34:35]
	v_pk_mul_f32 v[4:5], v[22:23], v[46:47]
	v_pk_mul_f32 v[6:7], v[6:7], v[28:29]
	v_pk_fma_f32 v[8:9], v[24:25], v[36:37], v[8:9] op_sel:[0,0,1] op_sel_hi:[1,1,0]
	v_pk_mov_b32 v[28:29], v[36:37], v[26:27] op_sel:[1,0]
	v_pk_fma_f32 v[4:5], v[22:23], v[48:49], v[4:5] op_sel:[0,0,1] op_sel_hi:[1,1,0]
	v_mov_b32_e32 v26, v49
	v_pk_fma_f32 v[8:9], v[12:13], v[28:29], v[8:9] op_sel_hi:[0,1,1]
	v_pk_fma_f32 v[4:5], v[16:17], v[26:27], v[4:5] op_sel_hi:[0,1,1]
	v_pk_add_f32 v[8:9], v[14:15], v[8:9] op_sel_hi:[0,1]
	v_pk_add_f32 v[4:5], v[10:11], v[4:5] op_sel_hi:[0,1]
	v_pk_mul_f32 v[4:5], v[8:9], v[4:5]
	v_and_b32_sdwa v0, v7, v220 dst_sel:DWORD dst_unused:UNUSED_PAD src0_sel:WORD_1 src1_sel:DWORD
	v_and_b32_sdwa v8, v6, v220 dst_sel:DWORD dst_unused:UNUSED_PAD src0_sel:WORD_1 src1_sel:DWORD
	s_lshl_b64 s[48:49], s[34:35], 15
	v_add3_u32 v6, v6, v8, s72
	v_add3_u32 v0, v7, v0, s72
	v_and_b32_sdwa v7, v5, v220 dst_sel:DWORD dst_unused:UNUSED_PAD src0_sel:WORD_1 src1_sel:DWORD
	v_and_b32_sdwa v8, v4, v220 dst_sel:DWORD dst_unused:UNUSED_PAD src0_sel:WORD_1 src1_sel:DWORD
	v_add3_u32 v5, v5, v7, s72
	v_add3_u32 v4, v4, v8, s72
	s_lshl_b64 s[48:49], s[48:49], 1
	v_add3_u32 v2, v2, v15, s72
	v_and_b32_e32 v5, 0xffff0000, v5
	v_and_b32_e32 v4, 0xffff0000, v4
	s_or_b32 s2, s48, 0x2000
	s_mov_b32 s3, s49
	v_or_b32_sdwa v2, v2, v11 dst_sel:DWORD dst_unused:UNUSED_PAD src0_sel:WORD_1 src1_sel:DWORD
	v_or_b32_sdwa v5, v5, v0 dst_sel:DWORD dst_unused:UNUSED_PAD src0_sel:DWORD src1_sel:WORD_1
	v_or_b32_sdwa v4, v4, v6 dst_sel:DWORD dst_unused:UNUSED_PAD src0_sel:DWORD src1_sel:WORD_1
	v_add_u32_e32 v0, 0, v141
	v_lshl_add_u64 v[26:27], v[124:125], 0, s[2:3]
	v_lshl_add_u64 v[28:29], v[126:127], 0, s[2:3]
	ds_write_b128 v0, v[2:5]
	v_mov_b64_e32 v[2:3], v[68:69]
	v_mov_b64_e32 v[4:5], v[70:71]
	v_mov_b64_e32 v[6:7], v[72:73]
	v_mov_b64_e32 v[8:9], v[74:75]
	v_mov_b32_e32 v34, 0
	v_mov_b32_e32 v38, 0
	v_mov_b32_e32 v36, 0
	s_and_saveexec_b64 s[50:51], s[40:41]
	s_cbranch_execz .LBB0_482
	v_mov_b32_e32 v11, v161
	v_mov_b32_e32 v13, v162
	s_waitcnt vmcnt(1)
	v_lshlrev_b32_e32 v38, 16, v11
	s_waitcnt vmcnt(0)
	v_lshlrev_b32_e32 v36, 16, v13
; #define LAS __attribute__((address_space(3)))
; __device__ __forceinline__ v4u pack8(const float (&f)[8]) { v4u o; o.x = pk2(f[0], f[1]); o.y = pk2(f[2], f[3]); o.z = pk2(f[4], f[5]); o.w = pk2(f[6], f[7]); return o; }
; __device__ __forceinline__ void phase_hyena(int l, LAS unsigned char* lds, int G) {
;     ...
;             for (int b = 0; b < 8; ++b) { const bf16r* xr = X1T + ((size_t)c * BATCH + b) * SEQ + tid * 8; const bf16r* vr = VT + ((size_t)c * BATCH + b) * SEQ + tid * 8;
;                 float xf[10], vf[10]; { float t8[8]; unpack8(*(const v4u*)xr, t8);
; #pragma unroll
;                     for (int e = 0; e < 8; ++e) xf[e + 1] = t8[e]; unpack8(*(const v4u*)vr, t8);
; #pragma unroll
;                     for (int e = 0; e < 8; ++e) vf[e + 1] = t8[e]; }
;                 xf[0] = tid > 0 ? bf1(xr[-1]) : 0.f; vf[0] = tid > 0 ? bf1(vr[-1]) : 0.f; xf[9] = tid < NTHR - 1 ? bf1(xr[8]) : 0.f; vf[9] = tid < NTHR - 1 ? bf1(vr[8]) : 0.f;
;                 float z[8];
; #pragma unroll
;                 for (int e = 0; e < 8; ++e) z[e] = (wx0 * xf[e] + wx1 * xf[e + 1] + wx2 * xf[e + 2] + bx) * (wv0 * vf[e] + wv1 * vf[e + 1] + wv2 * vf[e + 2] + bv);
;                 *(LAS v4u*)(Zs + b * ZPITCH + tid * 16) = pack8(z); }
.LBB0_482:
	s_or_b64 exec, exec, s[50:51]
	v_mov_b32_e32 v35, 0
	s_and_saveexec_b64 s[50:51], s[42:43]
	s_cbranch_execz .LBB0_484
	v_mov_b32_e32 v11, v163
	v_mov_b32_e32 v13, v164
	s_waitcnt vmcnt(1)
	v_lshlrev_b32_e32 v34, 16, v11
	s_waitcnt vmcnt(0)
	v_lshlrev_b32_e32 v35, 16, v13
.LBB0_484:
	s_or_b64 exec, exec, s[50:51]
	s_waitcnt vmcnt(1)
	v_and_b32_e32 v41, 0xffff0000, v2
	v_lshlrev_b32_e32 v43, 16, v3
	v_and_b32_e32 v47, 0xffff0000, v3
	s_waitcnt vmcnt(0)
	v_and_b32_e32 v3, 0xffff0000, v6
	v_mov_b32_e32 v32, v19
	v_mov_b32_e32 v33, v19
	v_mov_b32_e32 v28, v21
	v_mov_b32_e32 v29, v21
	v_mov_b32_e32 v42, v41
	v_lshlrev_b32_e32 v53, 16, v7
	v_mov_b32_e32 v52, v3
	v_and_b32_e32 v7, 0xffff0000, v7
	v_mov_b32_e32 v30, v18
	v_mov_b32_e32 v31, v18
	v_mov_b32_e32 v26, v20
	v_mov_b32_e32 v27, v20
	v_lshlrev_b32_e32 v40, 16, v2
	v_mov_b32_e32 v45, v43
	v_mov_b32_e32 v46, v43
	v_lshlrev_b32_e32 v2, 16, v6
	v_mov_b32_e32 v55, v53
	v_mov_b32_e32 v6, v53
	v_mov_b32_e32 v39, v47
	v_mov_b32_e32 v37, v7
	v_pk_mul_f32 v[42:43], v[32:33], v[42:43]
	v_pk_mul_f32 v[52:53], v[28:29], v[52:53]
	v_mov_b32_e32 v13, v12
	v_mov_b32_e32 v17, v16
	v_mov_b32_e32 v44, v40
	v_mov_b32_e32 v48, v41
	v_mov_b32_e32 v54, v2
	v_mov_b32_e32 v56, v3
	v_pk_mul_f32 v[38:39], v[18:19], v[38:39]
	v_pk_mul_f32 v[36:37], v[20:21], v[36:37]
	v_pk_fma_f32 v[40:41], v[30:31], v[40:41], v[42:43]
	v_pk_fma_f32 v[2:3], v[26:27], v[2:3], v[52:53]
	v_mov_b32_e32 v15, v14
	v_mov_b32_e32 v11, v10
	v_lshlrev_b32_e32 v49, 16, v4
	v_lshlrev_b32_e32 v57, 16, v8
	v_pk_fma_f32 v[40:41], v[12:13], v[46:47], v[40:41]
	v_pk_fma_f32 v[2:3], v[16:17], v[6:7], v[2:3]
	v_pk_fma_f32 v[38:39], v[24:25], v[44:45], v[38:39]
	v_pk_fma_f32 v[36:37], v[22:23], v[54:55], v[36:37]
	v_pk_add_f32 v[40:41], v[14:15], v[40:41]
	v_pk_add_f32 v[2:3], v[10:11], v[2:3]
	v_pk_fma_f32 v[38:39], v[12:13], v[48:49], v[38:39]
	v_pk_fma_f32 v[36:37], v[16:17], v[56:57], v[36:37]
	v_pk_mul_f32 v[2:3], v[40:41], v[2:3]
	v_pk_add_f32 v[38:39], v[14:15], v[38:39]
	v_pk_add_f32 v[36:37], v[10:11], v[36:37]
	v_lshlrev_b32_e32 v51, 16, v5
	v_pk_mul_f32 v[36:37], v[38:39], v[36:37]
	v_and_b32_sdwa v38, v2, v220 dst_sel:DWORD dst_unused:UNUSED_PAD src0_sel:WORD_1 src1_sel:DWORD
	v_and_b32_sdwa v6, v3, v220 dst_sel:DWORD dst_unused:UNUSED_PAD src0_sel:WORD_1 src1_sel:DWORD
	v_add3_u32 v2, v2, v38, s72
	v_and_b32_sdwa v38, v36, v220 dst_sel:DWORD dst_unused:UNUSED_PAD src0_sel:WORD_1 src1_sel:DWORD
	v_and_b32_e32 v5, 0xffff0000, v5
	v_and_b32_e32 v4, 0xffff0000, v4
	v_add3_u32 v3, v3, v6, s72
	v_and_b32_e32 v2, 0xffff0000, v2
	v_and_b32_sdwa v6, v37, v220 dst_sel:DWORD dst_unused:UNUSED_PAD src0_sel:WORD_1 src1_sel:DWORD
	v_add3_u32 v36, v36, v38, s72
	v_mov_b32_e32 v38, v49
	v_mov_b32_e32 v39, v51
	v_lshlrev_b32_e32 v59, 16, v9
	v_add3_u32 v6, v37, v6, s72
	v_or_b32_sdwa v2, v36, v2 dst_sel:DWORD dst_unused:UNUSED_PAD src0_sel:WORD_1 src1_sel:DWORD
	v_pk_mov_b32 v[36:37], v[46:47], v[4:5] op_sel:[1,0]
	v_pk_mul_f32 v[38:39], v[32:33], v[38:39]
	v_and_b32_e32 v9, 0xffff0000, v9
	v_and_b32_e32 v8, 0xffff0000, v8
	v_and_b32_e32 v6, 0xffff0000, v6
	v_pk_fma_f32 v[36:37], v[30:31], v[36:37], v[38:39]
	v_mov_b32_e32 v38, v57
	v_mov_b32_e32 v39, v59
	v_or_b32_sdwa v3, v6, v3 dst_sel:DWORD dst_unused:UNUSED_PAD src0_sel:DWORD src1_sel:WORD_1
	v_pk_mov_b32 v[6:7], v[6:7], v[8:9] op_sel:[1,0]
	v_pk_mul_f32 v[38:39], v[28:29], v[38:39]
	v_pk_fma_f32 v[36:37], v[12:13], v[4:5], v[36:37]
	v_pk_fma_f32 v[6:7], v[26:27], v[6:7], v[38:39]
	v_mov_b32_e32 v48, v5
	v_pk_fma_f32 v[6:7], v[16:17], v[8:9], v[6:7]
	v_mov_b32_e32 v56, v9
	v_mov_b32_e32 v50, v4
	v_mov_b32_e32 v58, v8
	v_pk_add_f32 v[36:37], v[14:15], v[36:37]
	v_pk_add_f32 v[6:7], v[10:11], v[6:7]
	v_pk_mul_f32 v[4:5], v[24:25], v[48:49]
	v_pk_mul_f32 v[8:9], v[22:23], v[56:57]
	v_pk_mul_f32 v[6:7], v[36:37], v[6:7]
	v_pk_fma_f32 v[4:5], v[24:25], v[50:51], v[4:5] op_sel:[0,0,1] op_sel_hi:[1,1,0]
	v_pk_mov_b32 v[36:37], v[50:51], v[34:35] op_sel:[1,0]
	v_pk_fma_f32 v[8:9], v[22:23], v[58:59], v[8:9] op_sel:[0,0,1] op_sel_hi:[1,1,0]
	v_mov_b32_e32 v34, v59
	v_pk_fma_f32 v[4:5], v[12:13], v[36:37], v[4:5]
	v_pk_fma_f32 v[8:9], v[16:17], v[34:35], v[8:9]
	v_pk_add_f32 v[4:5], v[14:15], v[4:5]
	v_pk_add_f32 v[8:9], v[10:11], v[8:9]
	s_or_b32 s2, s48, 0x4000
	v_pk_mul_f32 v[4:5], v[4:5], v[8:9]
	v_and_b32_sdwa v8, v7, v220 dst_sel:DWORD dst_unused:UNUSED_PAD src0_sel:WORD_1 src1_sel:DWORD
	v_and_b32_sdwa v9, v6, v220 dst_sel:DWORD dst_unused:UNUSED_PAD src0_sel:WORD_1 src1_sel:DWORD
	v_add3_u32 v6, v6, v9, s72
	v_add3_u32 v7, v7, v8, s72
	v_and_b32_sdwa v8, v5, v220 dst_sel:DWORD dst_unused:UNUSED_PAD src0_sel:WORD_1 src1_sel:DWORD
	v_and_b32_sdwa v9, v4, v220 dst_sel:DWORD dst_unused:UNUSED_PAD src0_sel:WORD_1 src1_sel:DWORD
	v_add3_u32 v5, v5, v8, s72
	v_add3_u32 v4, v4, v9, s72
	v_and_b32_e32 v5, 0xffff0000, v5
	v_and_b32_e32 v4, 0xffff0000, v4
	s_mov_b32 s3, s49
	v_or_b32_sdwa v5, v5, v7 dst_sel:DWORD dst_unused:UNUSED_PAD src0_sel:DWORD src1_sel:WORD_1
	v_or_b32_sdwa v4, v4, v6 dst_sel:DWORD dst_unused:UNUSED_PAD src0_sel:DWORD src1_sel:WORD_1
	v_lshl_add_u64 v[34:35], v[124:125], 0, s[2:3]
	v_lshl_add_u64 v[36:37], v[126:127], 0, s[2:3]
	ds_write_b128 v0, v[2:5] offset:8208
	v_mov_b64_e32 v[2:3], v[76:77]
	v_mov_b64_e32 v[4:5], v[78:79]
	v_mov_b64_e32 v[6:7], v[80:81]
	v_mov_b64_e32 v[8:9], v[82:83]
	v_mov_b32_e32 v38, 0
	v_mov_b32_e32 v42, 0
	v_mov_b32_e32 v40, 0
	s_and_saveexec_b64 s[50:51], s[40:41]
	s_cbranch_execz .LBB0_486
	v_mov_b32_e32 v39, v165
	v_mov_b32_e32 v40, v166
	s_waitcnt vmcnt(1)
	v_lshlrev_b32_e32 v42, 16, v39
	s_waitcnt vmcnt(0)
	v_lshlrev_b32_e32 v40, 16, v40
; #define LAS __attribute__((address_space(3)))
; __device__ __forceinline__ v4u pack8(const float (&f)[8]) { v4u o; o.x = pk2(f[0], f[1]); o.y = pk2(f[2], f[3]); o.z = pk2(f[4], f[5]); o.w = pk2(f[6], f[7]); return o; }
; __device__ __forceinline__ void phase_hyena(int l, LAS unsigned char* lds, int G) {
;     ...
;             for (int b = 0; b < 8; ++b) { const bf16r* xr = X1T + ((size_t)c * BATCH + b) * SEQ + tid * 8; const bf16r* vr = VT + ((size_t)c * BATCH + b) * SEQ + tid * 8;
;                 float xf[10], vf[10]; { float t8[8]; unpack8(*(const v4u*)xr, t8);
; #pragma unroll
;                     for (int e = 0; e < 8; ++e) xf[e + 1] = t8[e]; unpack8(*(const v4u*)vr, t8);
; #pragma unroll
;                     for (int e = 0; e < 8; ++e) vf[e + 1] = t8[e]; }
;                 xf[0] = tid > 0 ? bf1(xr[-1]) : 0.f; vf[0] = tid > 0 ? bf1(vr[-1]) : 0.f; xf[9] = tid < NTHR - 1 ? bf1(xr[8]) : 0.f; vf[9] = tid < NTHR - 1 ? bf1(vr[8]) : 0.f;
;                 float z[8];
; #pragma unroll
;                 for (int e = 0; e < 8; ++e) z[e] = (wx0 * xf[e] + wx1 * xf[e + 1] + wx2 * xf[e + 2] + bx) * (wv0 * vf[e] + wv1 * vf[e + 1] + wv2 * vf[e + 2] + bv);
;                 *(LAS v4u*)(Zs + b * ZPITCH + tid * 16) = pack8(z); }
.LBB0_486:
	s_or_b64 exec, exec, s[50:51]
	v_mov_b32_e32 v39, 0
	s_and_saveexec_b64 s[50:51], s[42:43]
	s_cbranch_execz .LBB0_488
	v_mov_b32_e32 v34, v167
	s_nop 0
	v_mov_b32_e32 v35, v168
	s_waitcnt vmcnt(1)
	v_lshlrev_b32_e32 v38, 16, v34
	s_waitcnt vmcnt(0)
	v_lshlrev_b32_e32 v39, 16, v35
.LBB0_488:
	s_or_b64 exec, exec, s[50:51]
	s_waitcnt vmcnt(1)
	v_and_b32_e32 v35, 0xffff0000, v2
	v_lshlrev_b32_e32 v37, 16, v3
	v_and_b32_e32 v47, 0xffff0000, v3
	s_waitcnt vmcnt(0)
	v_and_b32_e32 v3, 0xffff0000, v6
	v_mov_b32_e32 v36, v35
	v_lshlrev_b32_e32 v53, 16, v7
	v_mov_b32_e32 v52, v3
	v_lshlrev_b32_e32 v34, 16, v2
	v_mov_b32_e32 v45, v37
	v_mov_b32_e32 v46, v37
	v_lshlrev_b32_e32 v2, 16, v6
	v_mov_b32_e32 v55, v53
	v_mov_b32_e32 v6, v53
	v_pk_mul_f32 v[36:37], v[32:33], v[36:37]
	v_pk_mul_f32 v[52:53], v[28:29], v[52:53]
	v_mov_b32_e32 v44, v34
	v_mov_b32_e32 v48, v35
	v_mov_b32_e32 v54, v2
	v_and_b32_e32 v7, 0xffff0000, v7
	v_mov_b32_e32 v56, v3
	v_pk_fma_f32 v[34:35], v[30:31], v[34:35], v[36:37]
	v_pk_fma_f32 v[2:3], v[26:27], v[2:3], v[52:53]
	v_mov_b32_e32 v43, v47
	v_mov_b32_e32 v41, v7
	v_pk_fma_f32 v[34:35], v[12:13], v[46:47], v[34:35]
	v_pk_fma_f32 v[2:3], v[16:17], v[6:7], v[2:3]
	v_pk_mul_f32 v[42:43], v[18:19], v[42:43]
	v_pk_mul_f32 v[40:41], v[20:21], v[40:41]
	v_pk_add_f32 v[34:35], v[14:15], v[34:35]
	v_pk_add_f32 v[2:3], v[10:11], v[2:3]
	v_lshlrev_b32_e32 v49, 16, v4
	v_lshlrev_b32_e32 v57, 16, v8
	v_pk_mul_f32 v[2:3], v[34:35], v[2:3]
	v_pk_fma_f32 v[34:35], v[24:25], v[44:45], v[42:43]
	v_pk_fma_f32 v[36:37], v[22:23], v[54:55], v[40:41]
	v_pk_fma_f32 v[34:35], v[12:13], v[48:49], v[34:35]
	v_pk_fma_f32 v[36:37], v[16:17], v[56:57], v[36:37]
	v_pk_add_f32 v[34:35], v[14:15], v[34:35]
	v_pk_add_f32 v[36:37], v[10:11], v[36:37]
	v_lshlrev_b32_e32 v51, 16, v5
	v_pk_mul_f32 v[34:35], v[34:35], v[36:37]
	v_and_b32_sdwa v36, v2, v220 dst_sel:DWORD dst_unused:UNUSED_PAD src0_sel:WORD_1 src1_sel:DWORD
	v_and_b32_sdwa v6, v3, v220 dst_sel:DWORD dst_unused:UNUSED_PAD src0_sel:WORD_1 src1_sel:DWORD
	v_add3_u32 v2, v2, v36, s72
	v_and_b32_sdwa v36, v34, v220 dst_sel:DWORD dst_unused:UNUSED_PAD src0_sel:WORD_1 src1_sel:DWORD
	v_and_b32_e32 v5, 0xffff0000, v5
	v_and_b32_e32 v4, 0xffff0000, v4
	v_add3_u32 v3, v3, v6, s72
	v_and_b32_e32 v2, 0xffff0000, v2
	v_and_b32_sdwa v6, v35, v220 dst_sel:DWORD dst_unused:UNUSED_PAD src0_sel:WORD_1 src1_sel:DWORD
	v_add3_u32 v34, v34, v36, s72
	v_mov_b32_e32 v36, v49
	v_mov_b32_e32 v37, v51
	v_lshlrev_b32_e32 v59, 16, v9
	v_add3_u32 v6, v35, v6, s72
	v_or_b32_sdwa v2, v34, v2 dst_sel:DWORD dst_unused:UNUSED_PAD src0_sel:WORD_1 src1_sel:DWORD
	v_pk_mov_b32 v[34:35], v[46:47], v[4:5] op_sel:[1,0]
	v_pk_mul_f32 v[36:37], v[32:33], v[36:37]
	v_and_b32_e32 v9, 0xffff0000, v9
	v_and_b32_e32 v8, 0xffff0000, v8
	v_and_b32_e32 v6, 0xffff0000, v6
	v_pk_fma_f32 v[34:35], v[30:31], v[34:35], v[36:37]
	v_mov_b32_e32 v36, v57
	v_mov_b32_e32 v37, v59
	v_or_b32_sdwa v3, v6, v3 dst_sel:DWORD dst_unused:UNUSED_PAD src0_sel:DWORD src1_sel:WORD_1
	v_pk_mov_b32 v[6:7], v[6:7], v[8:9] op_sel:[1,0]
	v_pk_mul_f32 v[36:37], v[28:29], v[36:37]
	v_pk_fma_f32 v[34:35], v[12:13], v[4:5], v[34:35]
	v_pk_fma_f32 v[6:7], v[26:27], v[6:7], v[36:37]
	v_mov_b32_e32 v48, v5
	v_pk_fma_f32 v[6:7], v[16:17], v[8:9], v[6:7]
	v_mov_b32_e32 v56, v9
	v_mov_b32_e32 v50, v4
	v_mov_b32_e32 v58, v8
	v_pk_add_f32 v[34:35], v[14:15], v[34:35]
	v_pk_add_f32 v[6:7], v[10:11], v[6:7]
	v_pk_mul_f32 v[4:5], v[24:25], v[48:49]
	v_pk_mul_f32 v[8:9], v[22:23], v[56:57]
	v_pk_mul_f32 v[6:7], v[34:35], v[6:7]
	v_pk_fma_f32 v[4:5], v[24:25], v[50:51], v[4:5] op_sel:[0,0,1] op_sel_hi:[1,1,0]
	v_pk_mov_b32 v[34:35], v[50:51], v[38:39] op_sel:[1,0]
	v_pk_fma_f32 v[8:9], v[22:23], v[58:59], v[8:9] op_sel:[0,0,1] op_sel_hi:[1,1,0]
	v_mov_b32_e32 v38, v59
	v_pk_fma_f32 v[4:5], v[12:13], v[34:35], v[4:5]
	v_pk_fma_f32 v[8:9], v[16:17], v[38:39], v[8:9]
	v_pk_add_f32 v[4:5], v[14:15], v[4:5]
	v_pk_add_f32 v[8:9], v[10:11], v[8:9]
	s_or_b32 s2, s48, 0x6000
	v_pk_mul_f32 v[4:5], v[4:5], v[8:9]
	v_and_b32_sdwa v8, v7, v220 dst_sel:DWORD dst_unused:UNUSED_PAD src0_sel:WORD_1 src1_sel:DWORD
	v_and_b32_sdwa v9, v6, v220 dst_sel:DWORD dst_unused:UNUSED_PAD src0_sel:WORD_1 src1_sel:DWORD
	v_add3_u32 v6, v6, v9, s72
	v_add3_u32 v7, v7, v8, s72
	v_and_b32_sdwa v8, v5, v220 dst_sel:DWORD dst_unused:UNUSED_PAD src0_sel:WORD_1 src1_sel:DWORD
	v_and_b32_sdwa v9, v4, v220 dst_sel:DWORD dst_unused:UNUSED_PAD src0_sel:WORD_1 src1_sel:DWORD
	v_add3_u32 v5, v5, v8, s72
	v_add3_u32 v4, v4, v9, s72
	v_and_b32_e32 v5, 0xffff0000, v5
	v_and_b32_e32 v4, 0xffff0000, v4
	s_mov_b32 s3, s49
	v_or_b32_sdwa v5, v5, v7 dst_sel:DWORD dst_unused:UNUSED_PAD src0_sel:DWORD src1_sel:WORD_1
	v_or_b32_sdwa v4, v4, v6 dst_sel:DWORD dst_unused:UNUSED_PAD src0_sel:DWORD src1_sel:WORD_1
	v_lshl_add_u64 v[34:35], v[124:125], 0, s[2:3]
	v_lshl_add_u64 v[36:37], v[126:127], 0, s[2:3]
	ds_write_b128 v0, v[2:5] offset:16416
	v_mov_b64_e32 v[2:3], v[84:85]
	v_mov_b64_e32 v[4:5], v[86:87]
	v_mov_b64_e32 v[6:7], v[88:89]
	v_mov_b64_e32 v[8:9], v[90:91]
	v_mov_b32_e32 v38, 0
	v_mov_b32_e32 v42, 0
	v_mov_b32_e32 v40, 0
	s_and_saveexec_b64 s[50:51], s[40:41]
	s_cbranch_execz .LBB0_490
	v_mov_b32_e32 v39, v169
	v_mov_b32_e32 v40, v170
	s_waitcnt vmcnt(1)
	v_lshlrev_b32_e32 v42, 16, v39
	s_waitcnt vmcnt(0)
	v_lshlrev_b32_e32 v40, 16, v40
.LBB0_490:
	s_or_b64 exec, exec, s[50:51]
	v_mov_b32_e32 v39, 0
	s_and_saveexec_b64 s[50:51], s[42:43]
	s_cbranch_execz .LBB0_492
	v_mov_b32_e32 v34, v171
	s_nop 0
	v_mov_b32_e32 v35, v172
	s_waitcnt vmcnt(1)
	v_lshlrev_b32_e32 v38, 16, v34
	s_waitcnt vmcnt(0)
	v_lshlrev_b32_e32 v39, 16, v35
; #define LAS __attribute__((address_space(3)))
; __device__ __forceinline__ v4u pack8(const float (&f)[8]) { v4u o; o.x = pk2(f[0], f[1]); o.y = pk2(f[2], f[3]); o.z = pk2(f[4], f[5]); o.w = pk2(f[6], f[7]); return o; }
; __device__ __forceinline__ void phase_hyena(int l, LAS unsigned char* lds, int G) {
;     ...
;             for (int b = 0; b < 8; ++b) { const bf16r* xr = X1T + ((size_t)c * BATCH + b) * SEQ + tid * 8; const bf16r* vr = VT + ((size_t)c * BATCH + b) * SEQ + tid * 8;
;                 float xf[10], vf[10]; { float t8[8]; unpack8(*(const v4u*)xr, t8);
; #pragma unroll
;                     for (int e = 0; e < 8; ++e) xf[e + 1] = t8[e]; unpack8(*(const v4u*)vr, t8);
; #pragma unroll
;                     for (int e = 0; e < 8; ++e) vf[e + 1] = t8[e]; }
;                 xf[0] = tid > 0 ? bf1(xr[-1]) : 0.f; vf[0] = tid > 0 ? bf1(vr[-1]) : 0.f; xf[9] = tid < NTHR - 1 ? bf1(xr[8]) : 0.f; vf[9] = tid < NTHR - 1 ? bf1(vr[8]) : 0.f;
;                 float z[8];
; #pragma unroll
;                 for (int e = 0; e < 8; ++e) z[e] = (wx0 * xf[e] + wx1 * xf[e + 1] + wx2 * xf[e + 2] + bx) * (wv0 * vf[e] + wv1 * vf[e + 1] + wv2 * vf[e + 2] + bv);
;                 *(LAS v4u*)(Zs + b * ZPITCH + tid * 16) = pack8(z); }
.LBB0_492:
	s_or_b64 exec, exec, s[50:51]
	s_waitcnt vmcnt(1)
	v_and_b32_e32 v35, 0xffff0000, v2
	v_lshlrev_b32_e32 v37, 16, v3
	v_and_b32_e32 v47, 0xffff0000, v3
	s_waitcnt vmcnt(0)
	v_and_b32_e32 v3, 0xffff0000, v6
	v_mov_b32_e32 v36, v35
	v_lshlrev_b32_e32 v53, 16, v7
	v_mov_b32_e32 v52, v3
	v_lshlrev_b32_e32 v34, 16, v2
	v_mov_b32_e32 v45, v37
	v_mov_b32_e32 v46, v37
	v_lshlrev_b32_e32 v2, 16, v6
	v_mov_b32_e32 v55, v53
	v_mov_b32_e32 v6, v53
	v_pk_mul_f32 v[36:37], v[32:33], v[36:37]
	v_pk_mul_f32 v[52:53], v[28:29], v[52:53]
	v_mov_b32_e32 v44, v34
	v_mov_b32_e32 v48, v35
	v_mov_b32_e32 v54, v2
	v_and_b32_e32 v7, 0xffff0000, v7
	v_mov_b32_e32 v56, v3
	v_pk_fma_f32 v[34:35], v[30:31], v[34:35], v[36:37]
	v_pk_fma_f32 v[2:3], v[26:27], v[2:3], v[52:53]
	v_mov_b32_e32 v43, v47
	v_mov_b32_e32 v41, v7
	v_pk_fma_f32 v[34:35], v[12:13], v[46:47], v[34:35]
	v_pk_fma_f32 v[2:3], v[16:17], v[6:7], v[2:3]
	v_pk_mul_f32 v[42:43], v[18:19], v[42:43]
	v_pk_mul_f32 v[40:41], v[20:21], v[40:41]
	v_pk_add_f32 v[34:35], v[14:15], v[34:35]
	v_pk_add_f32 v[2:3], v[10:11], v[2:3]
	v_lshlrev_b32_e32 v49, 16, v4
	v_lshlrev_b32_e32 v57, 16, v8
	v_pk_mul_f32 v[2:3], v[34:35], v[2:3]
	v_pk_fma_f32 v[34:35], v[24:25], v[44:45], v[42:43]
	v_pk_fma_f32 v[36:37], v[22:23], v[54:55], v[40:41]
	v_pk_fma_f32 v[34:35], v[12:13], v[48:49], v[34:35]
	v_pk_fma_f32 v[36:37], v[16:17], v[56:57], v[36:37]
	v_pk_add_f32 v[34:35], v[14:15], v[34:35]
	v_pk_add_f32 v[36:37], v[10:11], v[36:37]
	v_lshlrev_b32_e32 v51, 16, v5
	v_pk_mul_f32 v[34:35], v[34:35], v[36:37]
	v_and_b32_sdwa v36, v2, v220 dst_sel:DWORD dst_unused:UNUSED_PAD src0_sel:WORD_1 src1_sel:DWORD
	v_and_b32_sdwa v6, v3, v220 dst_sel:DWORD dst_unused:UNUSED_PAD src0_sel:WORD_1 src1_sel:DWORD
	v_add3_u32 v2, v2, v36, s72
	v_and_b32_sdwa v36, v34, v220 dst_sel:DWORD dst_unused:UNUSED_PAD src0_sel:WORD_1 src1_sel:DWORD
	v_and_b32_e32 v5, 0xffff0000, v5
	v_and_b32_e32 v4, 0xffff0000, v4
	v_add3_u32 v3, v3, v6, s72
	v_and_b32_e32 v2, 0xffff0000, v2
	v_and_b32_sdwa v6, v35, v220 dst_sel:DWORD dst_unused:UNUSED_PAD src0_sel:WORD_1 src1_sel:DWORD
	v_add3_u32 v34, v34, v36, s72
	v_mov_b32_e32 v36, v49
	v_mov_b32_e32 v37, v51
	v_lshlrev_b32_e32 v59, 16, v9
	v_add3_u32 v6, v35, v6, s72
	v_or_b32_sdwa v2, v34, v2 dst_sel:DWORD dst_unused:UNUSED_PAD src0_sel:WORD_1 src1_sel:DWORD
	v_pk_mov_b32 v[34:35], v[46:47], v[4:5] op_sel:[1,0]
	v_pk_mul_f32 v[36:37], v[32:33], v[36:37]
	v_and_b32_e32 v9, 0xffff0000, v9
	v_and_b32_e32 v8, 0xffff0000, v8
	v_and_b32_e32 v6, 0xffff0000, v6
	v_pk_fma_f32 v[34:35], v[30:31], v[34:35], v[36:37]
	v_mov_b32_e32 v36, v57
	v_mov_b32_e32 v37, v59
	v_or_b32_sdwa v3, v6, v3 dst_sel:DWORD dst_unused:UNUSED_PAD src0_sel:DWORD src1_sel:WORD_1
	v_pk_mov_b32 v[6:7], v[6:7], v[8:9] op_sel:[1,0]
	v_pk_mul_f32 v[36:37], v[28:29], v[36:37]
	v_pk_fma_f32 v[34:35], v[12:13], v[4:5], v[34:35]
	v_pk_fma_f32 v[6:7], v[26:27], v[6:7], v[36:37]
	v_mov_b32_e32 v48, v5
	v_pk_fma_f32 v[6:7], v[16:17], v[8:9], v[6:7]
	v_mov_b32_e32 v56, v9
	v_mov_b32_e32 v50, v4
	v_mov_b32_e32 v58, v8
	v_pk_add_f32 v[34:35], v[14:15], v[34:35]
	v_pk_add_f32 v[6:7], v[10:11], v[6:7]
	v_pk_mul_f32 v[4:5], v[24:25], v[48:49]
	v_pk_mul_f32 v[8:9], v[22:23], v[56:57]
	v_pk_mul_f32 v[6:7], v[34:35], v[6:7]
	v_pk_fma_f32 v[4:5], v[24:25], v[50:51], v[4:5] op_sel:[0,0,1] op_sel_hi:[1,1,0]
	v_pk_mov_b32 v[34:35], v[50:51], v[38:39] op_sel:[1,0]
	v_pk_fma_f32 v[8:9], v[22:23], v[58:59], v[8:9] op_sel:[0,0,1] op_sel_hi:[1,1,0]
	v_mov_b32_e32 v38, v59
	v_pk_fma_f32 v[4:5], v[12:13], v[34:35], v[4:5]
	v_pk_fma_f32 v[8:9], v[16:17], v[38:39], v[8:9]
	v_pk_add_f32 v[4:5], v[14:15], v[4:5]
	v_pk_add_f32 v[8:9], v[10:11], v[8:9]
	s_or_b32 s2, s48, 0x8000
	v_pk_mul_f32 v[4:5], v[4:5], v[8:9]
	v_and_b32_sdwa v8, v7, v220 dst_sel:DWORD dst_unused:UNUSED_PAD src0_sel:WORD_1 src1_sel:DWORD
	v_and_b32_sdwa v9, v6, v220 dst_sel:DWORD dst_unused:UNUSED_PAD src0_sel:WORD_1 src1_sel:DWORD
	v_add3_u32 v6, v6, v9, s72
	v_add3_u32 v7, v7, v8, s72
	v_and_b32_sdwa v8, v5, v220 dst_sel:DWORD dst_unused:UNUSED_PAD src0_sel:WORD_1 src1_sel:DWORD
	v_and_b32_sdwa v9, v4, v220 dst_sel:DWORD dst_unused:UNUSED_PAD src0_sel:WORD_1 src1_sel:DWORD
	v_add3_u32 v5, v5, v8, s72
	v_add3_u32 v4, v4, v9, s72
	v_and_b32_e32 v5, 0xffff0000, v5
	v_and_b32_e32 v4, 0xffff0000, v4
	s_mov_b32 s3, s49
	v_or_b32_sdwa v5, v5, v7 dst_sel:DWORD dst_unused:UNUSED_PAD src0_sel:DWORD src1_sel:WORD_1
	v_or_b32_sdwa v4, v4, v6 dst_sel:DWORD dst_unused:UNUSED_PAD src0_sel:DWORD src1_sel:WORD_1
	v_lshl_add_u64 v[34:35], v[124:125], 0, s[2:3]
	v_lshl_add_u64 v[36:37], v[126:127], 0, s[2:3]
	ds_write_b128 v0, v[2:5] offset:24624
	v_mov_b64_e32 v[2:3], v[92:93]
	v_mov_b64_e32 v[4:5], v[94:95]
	v_mov_b64_e32 v[6:7], v[96:97]
	v_mov_b64_e32 v[8:9], v[98:99]
	v_mov_b32_e32 v38, 0
	v_mov_b32_e32 v42, 0
	v_mov_b32_e32 v40, 0
	s_and_saveexec_b64 s[50:51], s[40:41]
	s_cbranch_execz .LBB0_494
	v_mov_b32_e32 v39, v173
	v_mov_b32_e32 v40, v174
	s_waitcnt vmcnt(1)
	v_lshlrev_b32_e32 v42, 16, v39
	s_waitcnt vmcnt(0)
	v_lshlrev_b32_e32 v40, 16, v40
.LBB0_494:
	s_or_b64 exec, exec, s[50:51]
	v_mov_b32_e32 v39, 0
	s_and_saveexec_b64 s[50:51], s[42:43]
	s_cbranch_execz .LBB0_496
	v_mov_b32_e32 v34, v175
	s_nop 0
	v_mov_b32_e32 v35, v176
	s_waitcnt vmcnt(1)
	v_lshlrev_b32_e32 v38, 16, v34
	s_waitcnt vmcnt(0)
	v_lshlrev_b32_e32 v39, 16, v35
; #define LAS __attribute__((address_space(3)))
; __device__ __forceinline__ v4u pack8(const float (&f)[8]) { v4u o; o.x = pk2(f[0], f[1]); o.y = pk2(f[2], f[3]); o.z = pk2(f[4], f[5]); o.w = pk2(f[6], f[7]); return o; }
; __device__ __forceinline__ void phase_hyena(int l, LAS unsigned char* lds, int G) {
;     ...
;             for (int b = 0; b < 8; ++b) { const bf16r* xr = X1T + ((size_t)c * BATCH + b) * SEQ + tid * 8; const bf16r* vr = VT + ((size_t)c * BATCH + b) * SEQ + tid * 8;
;                 float xf[10], vf[10]; { float t8[8]; unpack8(*(const v4u*)xr, t8);
; #pragma unroll
;                     for (int e = 0; e < 8; ++e) xf[e + 1] = t8[e]; unpack8(*(const v4u*)vr, t8);
; #pragma unroll
;                     for (int e = 0; e < 8; ++e) vf[e + 1] = t8[e]; }
;                 xf[0] = tid > 0 ? bf1(xr[-1]) : 0.f; vf[0] = tid > 0 ? bf1(vr[-1]) : 0.f; xf[9] = tid < NTHR - 1 ? bf1(xr[8]) : 0.f; vf[9] = tid < NTHR - 1 ? bf1(vr[8]) : 0.f;
;                 float z[8];
; #pragma unroll
;                 for (int e = 0; e < 8; ++e) z[e] = (wx0 * xf[e] + wx1 * xf[e + 1] + wx2 * xf[e + 2] + bx) * (wv0 * vf[e] + wv1 * vf[e + 1] + wv2 * vf[e + 2] + bv);
;                 *(LAS v4u*)(Zs + b * ZPITCH + tid * 16) = pack8(z); }
.LBB0_496:
	s_or_b64 exec, exec, s[50:51]
	s_waitcnt vmcnt(1)
	v_and_b32_e32 v35, 0xffff0000, v2
	v_lshlrev_b32_e32 v37, 16, v3
	v_and_b32_e32 v47, 0xffff0000, v3
	s_waitcnt vmcnt(0)
	v_and_b32_e32 v3, 0xffff0000, v6
	v_mov_b32_e32 v36, v35
	v_lshlrev_b32_e32 v53, 16, v7
	v_mov_b32_e32 v52, v3
	v_lshlrev_b32_e32 v34, 16, v2
	v_mov_b32_e32 v45, v37
	v_mov_b32_e32 v46, v37
	v_lshlrev_b32_e32 v2, 16, v6
	v_mov_b32_e32 v55, v53
	v_mov_b32_e32 v6, v53
	v_pk_mul_f32 v[36:37], v[32:33], v[36:37]
	v_pk_mul_f32 v[52:53], v[28:29], v[52:53]
	v_mov_b32_e32 v44, v34
	v_mov_b32_e32 v48, v35
	v_mov_b32_e32 v54, v2
	v_and_b32_e32 v7, 0xffff0000, v7
	v_mov_b32_e32 v56, v3
	v_pk_fma_f32 v[34:35], v[30:31], v[34:35], v[36:37]
	v_pk_fma_f32 v[2:3], v[26:27], v[2:3], v[52:53]
	v_mov_b32_e32 v43, v47
	v_mov_b32_e32 v41, v7
	v_pk_fma_f32 v[34:35], v[12:13], v[46:47], v[34:35]
	v_pk_fma_f32 v[2:3], v[16:17], v[6:7], v[2:3]
	v_pk_mul_f32 v[42:43], v[18:19], v[42:43]
	v_pk_mul_f32 v[40:41], v[20:21], v[40:41]
	v_pk_add_f32 v[34:35], v[14:15], v[34:35]
	v_pk_add_f32 v[2:3], v[10:11], v[2:3]
	v_lshlrev_b32_e32 v49, 16, v4
	v_lshlrev_b32_e32 v57, 16, v8
	v_pk_mul_f32 v[2:3], v[34:35], v[2:3]
	v_pk_fma_f32 v[34:35], v[24:25], v[44:45], v[42:43]
	v_pk_fma_f32 v[36:37], v[22:23], v[54:55], v[40:41]
	v_pk_fma_f32 v[34:35], v[12:13], v[48:49], v[34:35]
	v_pk_fma_f32 v[36:37], v[16:17], v[56:57], v[36:37]
	v_pk_add_f32 v[34:35], v[14:15], v[34:35]
	v_pk_add_f32 v[36:37], v[10:11], v[36:37]
	v_lshlrev_b32_e32 v51, 16, v5
	v_pk_mul_f32 v[34:35], v[34:35], v[36:37]
	v_and_b32_sdwa v36, v2, v220 dst_sel:DWORD dst_unused:UNUSED_PAD src0_sel:WORD_1 src1_sel:DWORD
	v_and_b32_sdwa v6, v3, v220 dst_sel:DWORD dst_unused:UNUSED_PAD src0_sel:WORD_1 src1_sel:DWORD
	v_add3_u32 v2, v2, v36, s72
	v_and_b32_sdwa v36, v34, v220 dst_sel:DWORD dst_unused:UNUSED_PAD src0_sel:WORD_1 src1_sel:DWORD
	v_and_b32_e32 v5, 0xffff0000, v5
	v_and_b32_e32 v4, 0xffff0000, v4
	v_add3_u32 v3, v3, v6, s72
	v_and_b32_e32 v2, 0xffff0000, v2
	v_and_b32_sdwa v6, v35, v220 dst_sel:DWORD dst_unused:UNUSED_PAD src0_sel:WORD_1 src1_sel:DWORD
	v_add3_u32 v34, v34, v36, s72
	v_mov_b32_e32 v36, v49
	v_mov_b32_e32 v37, v51
	v_lshlrev_b32_e32 v59, 16, v9
	v_add3_u32 v6, v35, v6, s72
	v_or_b32_sdwa v2, v34, v2 dst_sel:DWORD dst_unused:UNUSED_PAD src0_sel:WORD_1 src1_sel:DWORD
	v_pk_mov_b32 v[34:35], v[46:47], v[4:5] op_sel:[1,0]
	v_pk_mul_f32 v[36:37], v[32:33], v[36:37]
	v_and_b32_e32 v9, 0xffff0000, v9
	v_and_b32_e32 v8, 0xffff0000, v8
	v_and_b32_e32 v6, 0xffff0000, v6
	v_pk_fma_f32 v[34:35], v[30:31], v[34:35], v[36:37]
	v_mov_b32_e32 v36, v57
	v_mov_b32_e32 v37, v59
	v_or_b32_sdwa v3, v6, v3 dst_sel:DWORD dst_unused:UNUSED_PAD src0_sel:DWORD src1_sel:WORD_1
	v_pk_mov_b32 v[6:7], v[6:7], v[8:9] op_sel:[1,0]
	v_pk_mul_f32 v[36:37], v[28:29], v[36:37]
	v_pk_fma_f32 v[34:35], v[12:13], v[4:5], v[34:35]
	v_pk_fma_f32 v[6:7], v[26:27], v[6:7], v[36:37]
	v_mov_b32_e32 v48, v5
	v_pk_fma_f32 v[6:7], v[16:17], v[8:9], v[6:7]
	v_mov_b32_e32 v56, v9
	v_mov_b32_e32 v50, v4
	v_mov_b32_e32 v58, v8
	v_pk_add_f32 v[34:35], v[14:15], v[34:35]
	v_pk_add_f32 v[6:7], v[10:11], v[6:7]
	v_pk_mul_f32 v[4:5], v[24:25], v[48:49]
	v_pk_mul_f32 v[8:9], v[22:23], v[56:57]
	v_pk_mul_f32 v[6:7], v[34:35], v[6:7]
	v_pk_fma_f32 v[4:5], v[24:25], v[50:51], v[4:5] op_sel:[0,0,1] op_sel_hi:[1,1,0]
	v_pk_mov_b32 v[34:35], v[50:51], v[38:39] op_sel:[1,0]
	v_pk_fma_f32 v[8:9], v[22:23], v[58:59], v[8:9] op_sel:[0,0,1] op_sel_hi:[1,1,0]
	v_mov_b32_e32 v38, v59
	v_pk_fma_f32 v[4:5], v[12:13], v[34:35], v[4:5]
	v_pk_fma_f32 v[8:9], v[16:17], v[38:39], v[8:9]
	v_pk_add_f32 v[4:5], v[14:15], v[4:5]
	v_pk_add_f32 v[8:9], v[10:11], v[8:9]
	s_or_b32 s2, s48, 0xa000
	v_pk_mul_f32 v[4:5], v[4:5], v[8:9]
	v_and_b32_sdwa v8, v7, v220 dst_sel:DWORD dst_unused:UNUSED_PAD src0_sel:WORD_1 src1_sel:DWORD
	v_and_b32_sdwa v9, v6, v220 dst_sel:DWORD dst_unused:UNUSED_PAD src0_sel:WORD_1 src1_sel:DWORD
	v_add3_u32 v6, v6, v9, s72
	v_add3_u32 v7, v7, v8, s72
	v_and_b32_sdwa v8, v5, v220 dst_sel:DWORD dst_unused:UNUSED_PAD src0_sel:WORD_1 src1_sel:DWORD
	v_and_b32_sdwa v9, v4, v220 dst_sel:DWORD dst_unused:UNUSED_PAD src0_sel:WORD_1 src1_sel:DWORD
	v_add3_u32 v5, v5, v8, s72
	v_add3_u32 v4, v4, v9, s72
	v_and_b32_e32 v5, 0xffff0000, v5
	v_and_b32_e32 v4, 0xffff0000, v4
	s_mov_b32 s3, s49
	v_or_b32_sdwa v5, v5, v7 dst_sel:DWORD dst_unused:UNUSED_PAD src0_sel:DWORD src1_sel:WORD_1
	v_or_b32_sdwa v4, v4, v6 dst_sel:DWORD dst_unused:UNUSED_PAD src0_sel:DWORD src1_sel:WORD_1
	v_lshl_add_u64 v[34:35], v[124:125], 0, s[2:3]
	v_lshl_add_u64 v[36:37], v[126:127], 0, s[2:3]
	ds_write_b128 v0, v[2:5] offset:32832
	v_mov_b64_e32 v[2:3], v[100:101]
	v_mov_b64_e32 v[4:5], v[102:103]
	v_mov_b64_e32 v[6:7], v[104:105]
	v_mov_b64_e32 v[8:9], v[106:107]
	v_mov_b32_e32 v38, 0
	v_mov_b32_e32 v42, 0
	v_mov_b32_e32 v40, 0
	s_and_saveexec_b64 s[50:51], s[40:41]
	s_cbranch_execz .LBB0_498
	v_mov_b32_e32 v39, v177
	v_mov_b32_e32 v40, v178
	s_waitcnt vmcnt(1)
	v_lshlrev_b32_e32 v42, 16, v39
	s_waitcnt vmcnt(0)
	v_lshlrev_b32_e32 v40, 16, v40
.LBB0_498:
	s_or_b64 exec, exec, s[50:51]
	v_mov_b32_e32 v39, 0
	s_and_saveexec_b64 s[50:51], s[42:43]
	s_cbranch_execz .LBB0_500
	v_mov_b32_e32 v34, v179
	s_nop 0
	v_mov_b32_e32 v35, v180
	s_waitcnt vmcnt(1)
	v_lshlrev_b32_e32 v38, 16, v34
	s_waitcnt vmcnt(0)
	v_lshlrev_b32_e32 v39, 16, v35
; #define LAS __attribute__((address_space(3)))
; __device__ __forceinline__ v4u pack8(const float (&f)[8]) { v4u o; o.x = pk2(f[0], f[1]); o.y = pk2(f[2], f[3]); o.z = pk2(f[4], f[5]); o.w = pk2(f[6], f[7]); return o; }
; __device__ __forceinline__ void phase_hyena(int l, LAS unsigned char* lds, int G) {
;     ...
;             for (int b = 0; b < 8; ++b) { const bf16r* xr = X1T + ((size_t)c * BATCH + b) * SEQ + tid * 8; const bf16r* vr = VT + ((size_t)c * BATCH + b) * SEQ + tid * 8;
;                 float xf[10], vf[10]; { float t8[8]; unpack8(*(const v4u*)xr, t8);
; #pragma unroll
;                     for (int e = 0; e < 8; ++e) xf[e + 1] = t8[e]; unpack8(*(const v4u*)vr, t8);
; #pragma unroll
;                     for (int e = 0; e < 8; ++e) vf[e + 1] = t8[e]; }
;                 xf[0] = tid > 0 ? bf1(xr[-1]) : 0.f; vf[0] = tid > 0 ? bf1(vr[-1]) : 0.f; xf[9] = tid < NTHR - 1 ? bf1(xr[8]) : 0.f; vf[9] = tid < NTHR - 1 ? bf1(vr[8]) : 0.f;
;                 float z[8];
; #pragma unroll
;                 for (int e = 0; e < 8; ++e) z[e] = (wx0 * xf[e] + wx1 * xf[e + 1] + wx2 * xf[e + 2] + bx) * (wv0 * vf[e] + wv1 * vf[e + 1] + wv2 * vf[e + 2] + bv);
;                 *(LAS v4u*)(Zs + b * ZPITCH + tid * 16) = pack8(z); }
.LBB0_500:
	s_or_b64 exec, exec, s[50:51]
	s_waitcnt vmcnt(1)
	v_and_b32_e32 v35, 0xffff0000, v2
	v_lshlrev_b32_e32 v37, 16, v3
	v_and_b32_e32 v47, 0xffff0000, v3
	s_waitcnt vmcnt(0)
	v_and_b32_e32 v3, 0xffff0000, v6
	v_mov_b32_e32 v36, v35
	v_lshlrev_b32_e32 v53, 16, v7
	v_mov_b32_e32 v52, v3
	v_lshlrev_b32_e32 v34, 16, v2
	v_mov_b32_e32 v45, v37
	v_mov_b32_e32 v46, v37
	v_lshlrev_b32_e32 v2, 16, v6
	v_mov_b32_e32 v55, v53
	v_mov_b32_e32 v6, v53
	v_pk_mul_f32 v[36:37], v[32:33], v[36:37]
	v_pk_mul_f32 v[52:53], v[28:29], v[52:53]
	v_mov_b32_e32 v44, v34
	v_mov_b32_e32 v48, v35
	v_mov_b32_e32 v54, v2
	v_and_b32_e32 v7, 0xffff0000, v7
	v_mov_b32_e32 v56, v3
	v_pk_fma_f32 v[34:35], v[30:31], v[34:35], v[36:37]
	v_pk_fma_f32 v[2:3], v[26:27], v[2:3], v[52:53]
	v_mov_b32_e32 v43, v47
	v_mov_b32_e32 v41, v7
	v_pk_fma_f32 v[34:35], v[12:13], v[46:47], v[34:35]
	v_pk_fma_f32 v[2:3], v[16:17], v[6:7], v[2:3]
	v_pk_mul_f32 v[42:43], v[18:19], v[42:43]
	v_pk_mul_f32 v[40:41], v[20:21], v[40:41]
	v_pk_add_f32 v[34:35], v[14:15], v[34:35]
	v_pk_add_f32 v[2:3], v[10:11], v[2:3]
	v_lshlrev_b32_e32 v49, 16, v4
	v_lshlrev_b32_e32 v57, 16, v8
	v_pk_mul_f32 v[2:3], v[34:35], v[2:3]
	v_pk_fma_f32 v[34:35], v[24:25], v[44:45], v[42:43]
	v_pk_fma_f32 v[36:37], v[22:23], v[54:55], v[40:41]
	v_pk_fma_f32 v[34:35], v[12:13], v[48:49], v[34:35]
	v_pk_fma_f32 v[36:37], v[16:17], v[56:57], v[36:37]
	v_pk_add_f32 v[34:35], v[14:15], v[34:35]
	v_pk_add_f32 v[36:37], v[10:11], v[36:37]
	v_lshlrev_b32_e32 v51, 16, v5
	v_pk_mul_f32 v[34:35], v[34:35], v[36:37]
	v_and_b32_sdwa v36, v2, v220 dst_sel:DWORD dst_unused:UNUSED_PAD src0_sel:WORD_1 src1_sel:DWORD
	v_and_b32_sdwa v6, v3, v220 dst_sel:DWORD dst_unused:UNUSED_PAD src0_sel:WORD_1 src1_sel:DWORD
	v_add3_u32 v2, v2, v36, s72
	v_and_b32_sdwa v36, v34, v220 dst_sel:DWORD dst_unused:UNUSED_PAD src0_sel:WORD_1 src1_sel:DWORD
	v_and_b32_e32 v5, 0xffff0000, v5
	v_and_b32_e32 v4, 0xffff0000, v4
	v_add3_u32 v3, v3, v6, s72
	v_and_b32_e32 v2, 0xffff0000, v2
	v_and_b32_sdwa v6, v35, v220 dst_sel:DWORD dst_unused:UNUSED_PAD src0_sel:WORD_1 src1_sel:DWORD
	v_add3_u32 v34, v34, v36, s72
	v_mov_b32_e32 v36, v49
	v_mov_b32_e32 v37, v51
	v_lshlrev_b32_e32 v59, 16, v9
	v_add3_u32 v6, v35, v6, s72
	v_or_b32_sdwa v2, v34, v2 dst_sel:DWORD dst_unused:UNUSED_PAD src0_sel:WORD_1 src1_sel:DWORD
	v_pk_mov_b32 v[34:35], v[46:47], v[4:5] op_sel:[1,0]
	v_pk_mul_f32 v[36:37], v[32:33], v[36:37]
	v_and_b32_e32 v9, 0xffff0000, v9
	v_and_b32_e32 v8, 0xffff0000, v8
	v_and_b32_e32 v6, 0xffff0000, v6
	v_pk_fma_f32 v[34:35], v[30:31], v[34:35], v[36:37]
	v_mov_b32_e32 v36, v57
	v_mov_b32_e32 v37, v59
	v_or_b32_sdwa v3, v6, v3 dst_sel:DWORD dst_unused:UNUSED_PAD src0_sel:DWORD src1_sel:WORD_1
	v_pk_mov_b32 v[6:7], v[6:7], v[8:9] op_sel:[1,0]
	v_pk_mul_f32 v[36:37], v[28:29], v[36:37]
	v_pk_fma_f32 v[34:35], v[12:13], v[4:5], v[34:35]
	v_pk_fma_f32 v[6:7], v[26:27], v[6:7], v[36:37]
	v_mov_b32_e32 v48, v5
	v_pk_fma_f32 v[6:7], v[16:17], v[8:9], v[6:7]
	v_mov_b32_e32 v56, v9
	v_mov_b32_e32 v50, v4
	v_mov_b32_e32 v58, v8
	v_pk_add_f32 v[34:35], v[14:15], v[34:35]
	v_pk_add_f32 v[6:7], v[10:11], v[6:7]
	v_pk_mul_f32 v[4:5], v[24:25], v[48:49]
	v_pk_mul_f32 v[8:9], v[22:23], v[56:57]
	v_pk_mul_f32 v[6:7], v[34:35], v[6:7]
	v_pk_fma_f32 v[4:5], v[24:25], v[50:51], v[4:5] op_sel:[0,0,1] op_sel_hi:[1,1,0]
	v_pk_mov_b32 v[34:35], v[50:51], v[38:39] op_sel:[1,0]
	v_pk_fma_f32 v[8:9], v[22:23], v[58:59], v[8:9] op_sel:[0,0,1] op_sel_hi:[1,1,0]
	v_mov_b32_e32 v38, v59
	v_pk_fma_f32 v[4:5], v[12:13], v[34:35], v[4:5]
	v_pk_fma_f32 v[8:9], v[16:17], v[38:39], v[8:9]
	v_pk_add_f32 v[4:5], v[14:15], v[4:5]
	v_pk_add_f32 v[8:9], v[10:11], v[8:9]
	s_or_b32 s2, s48, 0xc000
	v_pk_mul_f32 v[4:5], v[4:5], v[8:9]
	v_and_b32_sdwa v8, v7, v220 dst_sel:DWORD dst_unused:UNUSED_PAD src0_sel:WORD_1 src1_sel:DWORD
	v_and_b32_sdwa v9, v6, v220 dst_sel:DWORD dst_unused:UNUSED_PAD src0_sel:WORD_1 src1_sel:DWORD
	v_add3_u32 v6, v6, v9, s72
	v_add3_u32 v7, v7, v8, s72
	v_and_b32_sdwa v8, v5, v220 dst_sel:DWORD dst_unused:UNUSED_PAD src0_sel:WORD_1 src1_sel:DWORD
	v_and_b32_sdwa v9, v4, v220 dst_sel:DWORD dst_unused:UNUSED_PAD src0_sel:WORD_1 src1_sel:DWORD
	v_add3_u32 v5, v5, v8, s72
	v_add3_u32 v4, v4, v9, s72
	v_and_b32_e32 v5, 0xffff0000, v5
	v_and_b32_e32 v4, 0xffff0000, v4
	s_mov_b32 s3, s49
	v_or_b32_sdwa v5, v5, v7 dst_sel:DWORD dst_unused:UNUSED_PAD src0_sel:DWORD src1_sel:WORD_1
	v_or_b32_sdwa v4, v4, v6 dst_sel:DWORD dst_unused:UNUSED_PAD src0_sel:DWORD src1_sel:WORD_1
	v_lshl_add_u64 v[34:35], v[124:125], 0, s[2:3]
	v_lshl_add_u64 v[36:37], v[126:127], 0, s[2:3]
	ds_write_b128 v0, v[2:5] offset:41040
	v_mov_b64_e32 v[2:3], v[108:109]
	v_mov_b64_e32 v[4:5], v[110:111]
	v_mov_b64_e32 v[6:7], v[112:113]
	v_mov_b64_e32 v[8:9], v[114:115]
	v_mov_b32_e32 v38, 0
	v_mov_b32_e32 v42, 0
	v_mov_b32_e32 v40, 0
	s_and_saveexec_b64 s[50:51], s[40:41]
	s_cbranch_execz .LBB0_502
	v_mov_b32_e32 v39, v181
	v_mov_b32_e32 v40, v182
	s_waitcnt vmcnt(1)
	v_lshlrev_b32_e32 v42, 16, v39
	s_waitcnt vmcnt(0)
	v_lshlrev_b32_e32 v40, 16, v40
.LBB0_502:
	s_or_b64 exec, exec, s[50:51]
	v_mov_b32_e32 v39, 0
	s_and_saveexec_b64 s[50:51], s[42:43]
	s_cbranch_execz .LBB0_504
	v_mov_b32_e32 v34, v183
	s_nop 0
	v_mov_b32_e32 v35, v184
	s_waitcnt vmcnt(1)
	v_lshlrev_b32_e32 v38, 16, v34
	s_waitcnt vmcnt(0)
	v_lshlrev_b32_e32 v39, 16, v35
; #define LAS __attribute__((address_space(3)))
; __device__ __forceinline__ v4u pack8(const float (&f)[8]) { v4u o; o.x = pk2(f[0], f[1]); o.y = pk2(f[2], f[3]); o.z = pk2(f[4], f[5]); o.w = pk2(f[6], f[7]); return o; }
; __device__ __forceinline__ void phase_hyena(int l, LAS unsigned char* lds, int G) {
;     ...
;             for (int b = 0; b < 8; ++b) { const bf16r* xr = X1T + ((size_t)c * BATCH + b) * SEQ + tid * 8; const bf16r* vr = VT + ((size_t)c * BATCH + b) * SEQ + tid * 8;
;                 float xf[10], vf[10]; { float t8[8]; unpack8(*(const v4u*)xr, t8);
; #pragma unroll
;                     for (int e = 0; e < 8; ++e) xf[e + 1] = t8[e]; unpack8(*(const v4u*)vr, t8);
; #pragma unroll
;                     for (int e = 0; e < 8; ++e) vf[e + 1] = t8[e]; }
;                 xf[0] = tid > 0 ? bf1(xr[-1]) : 0.f; vf[0] = tid > 0 ? bf1(vr[-1]) : 0.f; xf[9] = tid < NTHR - 1 ? bf1(xr[8]) : 0.f; vf[9] = tid < NTHR - 1 ? bf1(vr[8]) : 0.f;
;                 float z[8];
; #pragma unroll
;                 for (int e = 0; e < 8; ++e) z[e] = (wx0 * xf[e] + wx1 * xf[e + 1] + wx2 * xf[e + 2] + bx) * (wv0 * vf[e] + wv1 * vf[e + 1] + wv2 * vf[e + 2] + bv);
;                 *(LAS v4u*)(Zs + b * ZPITCH + tid * 16) = pack8(z); }
.LBB0_504:
	s_or_b64 exec, exec, s[50:51]
	s_waitcnt vmcnt(1)
	v_and_b32_e32 v35, 0xffff0000, v2
	v_lshlrev_b32_e32 v37, 16, v3
	v_and_b32_e32 v47, 0xffff0000, v3
	s_waitcnt vmcnt(0)
	v_and_b32_e32 v3, 0xffff0000, v6
	v_mov_b32_e32 v36, v35
	v_lshlrev_b32_e32 v53, 16, v7
	v_mov_b32_e32 v52, v3
	v_lshlrev_b32_e32 v34, 16, v2
	v_mov_b32_e32 v45, v37
	v_mov_b32_e32 v46, v37
	v_lshlrev_b32_e32 v2, 16, v6
	v_mov_b32_e32 v55, v53
	v_mov_b32_e32 v6, v53
	v_pk_mul_f32 v[36:37], v[32:33], v[36:37]
	v_pk_mul_f32 v[52:53], v[28:29], v[52:53]
	v_mov_b32_e32 v44, v34
	v_mov_b32_e32 v48, v35
	v_mov_b32_e32 v54, v2
	v_and_b32_e32 v7, 0xffff0000, v7
	v_mov_b32_e32 v56, v3
	v_pk_fma_f32 v[34:35], v[30:31], v[34:35], v[36:37]
	v_pk_fma_f32 v[2:3], v[26:27], v[2:3], v[52:53]
	v_mov_b32_e32 v43, v47
	v_mov_b32_e32 v41, v7
	v_pk_fma_f32 v[34:35], v[12:13], v[46:47], v[34:35]
	v_pk_fma_f32 v[2:3], v[16:17], v[6:7], v[2:3]
	v_pk_mul_f32 v[42:43], v[18:19], v[42:43]
	v_pk_mul_f32 v[40:41], v[20:21], v[40:41]
	v_pk_add_f32 v[34:35], v[14:15], v[34:35]
	v_pk_add_f32 v[2:3], v[10:11], v[2:3]
	v_lshlrev_b32_e32 v49, 16, v4
	v_lshlrev_b32_e32 v57, 16, v8
	v_pk_mul_f32 v[2:3], v[34:35], v[2:3]
	v_pk_fma_f32 v[34:35], v[24:25], v[44:45], v[42:43]
	v_pk_fma_f32 v[36:37], v[22:23], v[54:55], v[40:41]
	v_pk_fma_f32 v[34:35], v[12:13], v[48:49], v[34:35]
	v_pk_fma_f32 v[36:37], v[16:17], v[56:57], v[36:37]
	v_pk_add_f32 v[34:35], v[14:15], v[34:35]
	v_pk_add_f32 v[36:37], v[10:11], v[36:37]
	v_lshlrev_b32_e32 v51, 16, v5
	v_pk_mul_f32 v[34:35], v[34:35], v[36:37]
	v_and_b32_sdwa v36, v2, v220 dst_sel:DWORD dst_unused:UNUSED_PAD src0_sel:WORD_1 src1_sel:DWORD
	v_and_b32_sdwa v6, v3, v220 dst_sel:DWORD dst_unused:UNUSED_PAD src0_sel:WORD_1 src1_sel:DWORD
	v_add3_u32 v2, v2, v36, s72
	v_and_b32_sdwa v36, v34, v220 dst_sel:DWORD dst_unused:UNUSED_PAD src0_sel:WORD_1 src1_sel:DWORD
	v_and_b32_e32 v5, 0xffff0000, v5
	v_and_b32_e32 v4, 0xffff0000, v4
	v_add3_u32 v3, v3, v6, s72
	v_and_b32_e32 v2, 0xffff0000, v2
	v_and_b32_sdwa v6, v35, v220 dst_sel:DWORD dst_unused:UNUSED_PAD src0_sel:WORD_1 src1_sel:DWORD
	v_add3_u32 v34, v34, v36, s72
	v_mov_b32_e32 v36, v49
	v_mov_b32_e32 v37, v51
	v_lshlrev_b32_e32 v59, 16, v9
	v_add3_u32 v6, v35, v6, s72
	v_or_b32_sdwa v2, v34, v2 dst_sel:DWORD dst_unused:UNUSED_PAD src0_sel:WORD_1 src1_sel:DWORD
	v_pk_mov_b32 v[34:35], v[46:47], v[4:5] op_sel:[1,0]
	v_pk_mul_f32 v[36:37], v[32:33], v[36:37]
	v_and_b32_e32 v9, 0xffff0000, v9
	v_and_b32_e32 v8, 0xffff0000, v8
	v_and_b32_e32 v6, 0xffff0000, v6
	v_pk_fma_f32 v[34:35], v[30:31], v[34:35], v[36:37]
	v_mov_b32_e32 v36, v57
	v_mov_b32_e32 v37, v59
	v_or_b32_sdwa v3, v6, v3 dst_sel:DWORD dst_unused:UNUSED_PAD src0_sel:DWORD src1_sel:WORD_1
	v_pk_mov_b32 v[6:7], v[6:7], v[8:9] op_sel:[1,0]
	v_pk_mul_f32 v[36:37], v[28:29], v[36:37]
	v_pk_fma_f32 v[34:35], v[12:13], v[4:5], v[34:35]
	v_pk_fma_f32 v[6:7], v[26:27], v[6:7], v[36:37]
	v_mov_b32_e32 v48, v5
	v_pk_fma_f32 v[6:7], v[16:17], v[8:9], v[6:7]
	v_mov_b32_e32 v56, v9
	v_mov_b32_e32 v50, v4
	v_mov_b32_e32 v58, v8
	v_pk_add_f32 v[34:35], v[14:15], v[34:35]
	v_pk_add_f32 v[6:7], v[10:11], v[6:7]
	v_pk_mul_f32 v[4:5], v[24:25], v[48:49]
	v_pk_mul_f32 v[8:9], v[22:23], v[56:57]
	v_pk_mul_f32 v[6:7], v[34:35], v[6:7]
	v_pk_fma_f32 v[4:5], v[24:25], v[50:51], v[4:5] op_sel:[0,0,1] op_sel_hi:[1,1,0]
	v_pk_mov_b32 v[34:35], v[50:51], v[38:39] op_sel:[1,0]
	v_pk_fma_f32 v[8:9], v[22:23], v[58:59], v[8:9] op_sel:[0,0,1] op_sel_hi:[1,1,0]
	v_mov_b32_e32 v38, v59
	v_pk_fma_f32 v[4:5], v[12:13], v[34:35], v[4:5]
	v_pk_fma_f32 v[8:9], v[16:17], v[38:39], v[8:9]
	v_pk_add_f32 v[4:5], v[14:15], v[4:5]
	v_pk_add_f32 v[8:9], v[10:11], v[8:9]
	s_or_b32 s48, s48, 0xe000
	v_pk_mul_f32 v[4:5], v[4:5], v[8:9]
	v_and_b32_sdwa v8, v7, v220 dst_sel:DWORD dst_unused:UNUSED_PAD src0_sel:WORD_1 src1_sel:DWORD
	v_and_b32_sdwa v9, v6, v220 dst_sel:DWORD dst_unused:UNUSED_PAD src0_sel:WORD_1 src1_sel:DWORD
	v_add3_u32 v6, v6, v9, s72
	v_add3_u32 v7, v7, v8, s72
	v_and_b32_sdwa v8, v5, v220 dst_sel:DWORD dst_unused:UNUSED_PAD src0_sel:WORD_1 src1_sel:DWORD
	v_and_b32_sdwa v9, v4, v220 dst_sel:DWORD dst_unused:UNUSED_PAD src0_sel:WORD_1 src1_sel:DWORD
	v_add3_u32 v5, v5, v8, s72
	v_add3_u32 v4, v4, v9, s72
	v_and_b32_e32 v5, 0xffff0000, v5
	v_and_b32_e32 v4, 0xffff0000, v4
	v_or_b32_sdwa v5, v5, v7 dst_sel:DWORD dst_unused:UNUSED_PAD src0_sel:DWORD src1_sel:WORD_1
	v_or_b32_sdwa v4, v4, v6 dst_sel:DWORD dst_unused:UNUSED_PAD src0_sel:DWORD src1_sel:WORD_1
	v_lshl_add_u64 v[34:35], v[124:125], 0, s[48:49]
	v_lshl_add_u64 v[36:37], v[126:127], 0, s[48:49]
	ds_write_b128 v0, v[2:5] offset:49248
	v_mov_b64_e32 v[2:3], v[116:117]
	v_mov_b64_e32 v[4:5], v[118:119]
	v_mov_b64_e32 v[6:7], v[120:121]
	v_mov_b64_e32 v[8:9], v[122:123]
	v_mov_b32_e32 v38, 0
	v_mov_b32_e32 v42, 0
	v_mov_b32_e32 v40, 0
	s_and_saveexec_b64 s[48:49], s[40:41]
	s_cbranch_execz .LBB0_506
	v_mov_b32_e32 v39, v185
	v_mov_b32_e32 v40, v186
	s_waitcnt vmcnt(1)
	v_lshlrev_b32_e32 v42, 16, v39
	s_waitcnt vmcnt(0)
	v_lshlrev_b32_e32 v40, 16, v40
.LBB0_506:
	s_or_b64 exec, exec, s[48:49]
	v_mov_b32_e32 v39, 0
	s_and_saveexec_b64 s[48:49], s[42:43]
	s_cbranch_execz .LBB0_508
	v_mov_b32_e32 v34, v187
	s_nop 0
	v_mov_b32_e32 v35, v188
	s_waitcnt vmcnt(1)
	v_lshlrev_b32_e32 v38, 16, v34
	s_waitcnt vmcnt(0)
	v_lshlrev_b32_e32 v39, 16, v35
; #define LAS __attribute__((address_space(3)))
; __device__ __forceinline__ v4u pack8(const float (&f)[8]) { v4u o; o.x = pk2(f[0], f[1]); o.y = pk2(f[2], f[3]); o.z = pk2(f[4], f[5]); o.w = pk2(f[6], f[7]); return o; }
; __device__ __forceinline__ void phase_hyena(int l, LAS unsigned char* lds, int G) {
;     ...
;                 xf[0] = tid > 0 ? bf1(xr[-1]) : 0.f; vf[0] = tid > 0 ? bf1(vr[-1]) : 0.f; xf[9] = tid < NTHR - 1 ? bf1(xr[8]) : 0.f; vf[9] = tid < NTHR - 1 ? bf1(vr[8]) : 0.f;
;                 float z[8];
; #pragma unroll
;                 for (int e = 0; e < 8; ++e) z[e] = (wx0 * xf[e] + wx1 * xf[e + 1] + wx2 * xf[e + 2] + bx) * (wv0 * vf[e] + wv1 * vf[e + 1] + wv2 * vf[e + 2] + bv);
;                 *(LAS v4u*)(Zs + b * ZPITCH + tid * 16) = pack8(z); }
;         }
; #pragma unroll
;         for (int i = 0; i < 2; ++i) { *(LAS v4u*)((LAS unsigned char*)rl + (i * NTHR + tid) * 16) = *(const v4u*)(RG + (size_t)c * 8192 + (i * NTHR + tid) * 8);
;             *(LAS v4u*)((LAS unsigned char*)rl + RG1_LDS + (i * NTHR + tid) * 16) = *(const v4u*)(RG1 + (size_t)c * 8192 + (i * NTHR + tid) * 8); }
;         __syncthreads();
;         const float invn = 1.0f / NORM[c], bias = hb[c];
;         f32x16 acc[2][2];
; #pragma unroll
;         for (int a = 0; a < 2; ++a)
; #pragma unroll
;             for (int bb = 0; bb < 2; ++bb) acc[a][bb] = f32x16{};
.LBB0_508:
	s_or_b64 exec, exec, s[48:49]
	s_waitcnt vmcnt(1)
	v_and_b32_e32 v35, 0xffff0000, v2
	v_lshlrev_b32_e32 v37, 16, v3
	v_and_b32_e32 v47, 0xffff0000, v3
	s_waitcnt vmcnt(0)
	v_and_b32_e32 v3, 0xffff0000, v6
	v_lshlrev_b32_e32 v53, 16, v7
	v_and_b32_e32 v7, 0xffff0000, v7
	v_mov_b32_e32 v36, v35
	v_mov_b32_e32 v52, v3
	v_mov_b32_e32 v41, v7
	v_lshlrev_b32_e32 v34, 16, v2
	v_mov_b32_e32 v45, v37
	v_mov_b32_e32 v46, v37
	v_lshlrev_b32_e32 v2, 16, v6
	v_mov_b32_e32 v43, v47
	v_pk_mul_f32 v[20:21], v[20:21], v[40:41]
	v_pk_mul_f32 v[36:37], v[32:33], v[36:37]
	v_pk_mul_f32 v[40:41], v[28:29], v[52:53]
	v_mov_b32_e32 v44, v34
	v_mov_b32_e32 v48, v35
	v_mov_b32_e32 v54, v2
	v_mov_b32_e32 v55, v53
	v_mov_b32_e32 v6, v53
	v_mov_b32_e32 v56, v3
	v_pk_mul_f32 v[18:19], v[18:19], v[42:43]
	v_pk_fma_f32 v[34:35], v[30:31], v[34:35], v[36:37]
	v_pk_fma_f32 v[2:3], v[26:27], v[2:3], v[40:41]
	v_lshlrev_b32_e32 v49, 16, v4
	v_lshlrev_b32_e32 v57, 16, v8
	v_pk_fma_f32 v[34:35], v[12:13], v[46:47], v[34:35]
	v_pk_fma_f32 v[2:3], v[16:17], v[6:7], v[2:3]
	v_pk_fma_f32 v[18:19], v[24:25], v[44:45], v[18:19]
	v_pk_fma_f32 v[20:21], v[22:23], v[54:55], v[20:21]
	v_pk_add_f32 v[34:35], v[14:15], v[34:35]
	v_pk_add_f32 v[2:3], v[10:11], v[2:3]
	v_pk_fma_f32 v[18:19], v[12:13], v[48:49], v[18:19]
	v_pk_fma_f32 v[20:21], v[16:17], v[56:57], v[20:21]
	v_pk_mul_f32 v[2:3], v[34:35], v[2:3]
	v_pk_add_f32 v[18:19], v[14:15], v[18:19]
	v_pk_add_f32 v[20:21], v[10:11], v[20:21]
	v_lshlrev_b32_e32 v51, 16, v5
	v_pk_mul_f32 v[18:19], v[18:19], v[20:21]
	v_and_b32_sdwa v20, v2, v220 dst_sel:DWORD dst_unused:UNUSED_PAD src0_sel:WORD_1 src1_sel:DWORD
	v_and_b32_sdwa v6, v3, v220 dst_sel:DWORD dst_unused:UNUSED_PAD src0_sel:WORD_1 src1_sel:DWORD
	v_add3_u32 v2, v2, v20, s72
	v_and_b32_sdwa v20, v18, v220 dst_sel:DWORD dst_unused:UNUSED_PAD src0_sel:WORD_1 src1_sel:DWORD
	v_and_b32_e32 v5, 0xffff0000, v5
	v_and_b32_e32 v4, 0xffff0000, v4
	v_add3_u32 v3, v3, v6, s72
	v_and_b32_e32 v2, 0xffff0000, v2
	v_and_b32_sdwa v6, v19, v220 dst_sel:DWORD dst_unused:UNUSED_PAD src0_sel:WORD_1 src1_sel:DWORD
	v_add3_u32 v18, v18, v20, s72
	v_mov_b32_e32 v20, v49
	v_mov_b32_e32 v21, v51
	v_lshlrev_b32_e32 v59, 16, v9
	v_add3_u32 v6, v19, v6, s72
	v_or_b32_sdwa v2, v18, v2 dst_sel:DWORD dst_unused:UNUSED_PAD src0_sel:WORD_1 src1_sel:DWORD
	v_pk_mov_b32 v[18:19], v[46:47], v[4:5] op_sel:[1,0]
	v_pk_mul_f32 v[20:21], v[32:33], v[20:21]
	v_and_b32_e32 v9, 0xffff0000, v9
	v_and_b32_e32 v8, 0xffff0000, v8
	v_and_b32_e32 v6, 0xffff0000, v6
	v_pk_fma_f32 v[18:19], v[30:31], v[18:19], v[20:21]
	v_mov_b32_e32 v20, v57
	v_mov_b32_e32 v21, v59
	v_or_b32_sdwa v3, v6, v3 dst_sel:DWORD dst_unused:UNUSED_PAD src0_sel:DWORD src1_sel:WORD_1
	v_pk_mov_b32 v[6:7], v[6:7], v[8:9] op_sel:[1,0]
	v_pk_mul_f32 v[20:21], v[28:29], v[20:21]
	v_pk_fma_f32 v[18:19], v[12:13], v[4:5], v[18:19]
	v_pk_fma_f32 v[6:7], v[26:27], v[6:7], v[20:21]
	v_mov_b32_e32 v48, v5
	v_pk_fma_f32 v[6:7], v[16:17], v[8:9], v[6:7]
	v_mov_b32_e32 v56, v9
	v_mov_b32_e32 v50, v4
	v_mov_b32_e32 v58, v8
	v_pk_add_f32 v[18:19], v[14:15], v[18:19]
	v_pk_add_f32 v[6:7], v[10:11], v[6:7]
	v_pk_mul_f32 v[4:5], v[24:25], v[48:49]
	v_pk_mul_f32 v[8:9], v[22:23], v[56:57]
	v_pk_mul_f32 v[6:7], v[18:19], v[6:7]
	v_pk_fma_f32 v[4:5], v[24:25], v[50:51], v[4:5] op_sel:[0,0,1] op_sel_hi:[1,1,0]
	v_pk_mov_b32 v[18:19], v[50:51], v[38:39] op_sel:[1,0]
	v_pk_fma_f32 v[8:9], v[22:23], v[58:59], v[8:9] op_sel:[0,0,1] op_sel_hi:[1,1,0]
	v_mov_b32_e32 v38, v59
	v_pk_fma_f32 v[4:5], v[12:13], v[18:19], v[4:5]
	v_pk_fma_f32 v[8:9], v[16:17], v[38:39], v[8:9]
	v_pk_add_f32 v[4:5], v[14:15], v[4:5]
	v_pk_add_f32 v[8:9], v[10:11], v[8:9]
	s_lshl_b64 s[2:3], s[34:35], 14
	v_pk_mul_f32 v[4:5], v[4:5], v[8:9]
	v_and_b32_sdwa v8, v7, v220 dst_sel:DWORD dst_unused:UNUSED_PAD src0_sel:WORD_1 src1_sel:DWORD
	v_and_b32_sdwa v9, v6, v220 dst_sel:DWORD dst_unused:UNUSED_PAD src0_sel:WORD_1 src1_sel:DWORD
	v_add3_u32 v6, v6, v9, s72
	v_add3_u32 v7, v7, v8, s72
	v_and_b32_sdwa v8, v5, v220 dst_sel:DWORD dst_unused:UNUSED_PAD src0_sel:WORD_1 src1_sel:DWORD
	v_and_b32_sdwa v9, v4, v220 dst_sel:DWORD dst_unused:UNUSED_PAD src0_sel:WORD_1 src1_sel:DWORD
	v_add3_u32 v5, v5, v8, s72
	v_add3_u32 v4, v4, v9, s72
	v_and_b32_e32 v5, 0xffff0000, v5
	v_and_b32_e32 v4, 0xffff0000, v4
	s_add_u32 s14, s62, s2
	v_or_b32_sdwa v5, v5, v7 dst_sel:DWORD dst_unused:UNUSED_PAD src0_sel:DWORD src1_sel:WORD_1
	v_or_b32_sdwa v4, v4, v6 dst_sel:DWORD dst_unused:UNUSED_PAD src0_sel:DWORD src1_sel:WORD_1
	s_addc_u32 s15, s63, s3
	ds_write_b128 v0, v[2:5] offset:57456
	v_lshl_add_u64 v[2:3], s[14:15], 0, v[136:137]
	v_mov_b64_e32 v[2:3], v[202:203]
	v_mov_b64_e32 v[4:5], v[204:205]
	s_add_u32 s2, s64, s2
	v_readlane_b32 s28, v247, 30
	s_addc_u32 s3, s65, s3
	v_readlane_b32 s29, v247, 31
	v_add_u32_e32 v0, s28, v141
	s_waitcnt vmcnt(0)
	ds_write_b128 v0, v[2:5]
	v_lshl_add_u64 v[2:3], s[2:3], 0, v[136:137]
	v_mov_b64_e32 v[2:3], v[206:207]
	v_mov_b64_e32 v[4:5], v[208:209]
	v_add_u32_e32 v0, s29, v141
	s_waitcnt vmcnt(0)
	ds_write_b128 v0, v[2:5]
	v_lshl_add_u64 v[2:3], s[14:15], 0, v[138:139]
	v_mov_b64_e32 v[2:3], v[210:211]
	v_mov_b64_e32 v[4:5], v[212:213]
	v_add_u32_e32 v0, s28, v129
	s_waitcnt vmcnt(0)
	ds_write_b128 v0, v[2:5]
	v_lshl_add_u64 v[2:3], s[2:3], 0, v[138:139]
	v_mov_b64_e32 v[2:3], v[214:215]
	v_mov_b64_e32 v[4:5], v[216:217]
	s_add_u32 s2, s66, s46
	v_add_u32_e32 v0, s29, v129
	s_addc_u32 s3, s67, s47
	s_waitcnt vmcnt(0)
	ds_write_b128 v0, v[2:5]
	s_waitcnt lgkmcnt(0)
	s_barrier
	global_load_dword v154, v1, s[2:3]
	s_add_u32 s2, s68, s46
	s_addc_u32 s3, s69, s47
	global_load_dword v140, v1, s[2:3]
	s_andn2_b64 vcc, exec, s[16:17]
	s_cbranch_vccnz .LBB0_519
	v_mov_b32_e32 v16, 0
	v_mov_b32_e32 v0, v145
	v_mov_b32_e32 v14, v144
	v_mov_b32_e32 v15, v143
	s_mov_b32 s2, s70
	v_mov_b32_e32 v17, v16
	v_mov_b32_e32 v18, v16
	v_mov_b32_e32 v19, v16
	v_mov_b32_e32 v20, v16
	v_mov_b32_e32 v21, v16
	v_mov_b32_e32 v22, v16
	v_mov_b32_e32 v23, v16
	v_mov_b32_e32 v24, v16
	v_mov_b32_e32 v25, v16
	v_mov_b32_e32 v26, v16
	v_mov_b32_e32 v27, v16
	v_mov_b32_e32 v28, v16
	v_mov_b32_e32 v29, v16
	v_mov_b32_e32 v30, v16
	v_mov_b32_e32 v31, v16
	v_mov_b32_e32 v48, v16
	v_mov_b32_e32 v49, v16
	v_mov_b32_e32 v50, v16
	v_mov_b32_e32 v51, v16
	v_mov_b32_e32 v52, v16
	v_mov_b32_e32 v53, v16
	v_mov_b32_e32 v54, v16
	v_mov_b32_e32 v55, v16
	v_mov_b32_e32 v56, v16
	v_mov_b32_e32 v57, v16
	v_mov_b32_e32 v58, v16
	v_mov_b32_e32 v59, v16
	v_mov_b32_e32 v60, v16
	v_mov_b32_e32 v61, v16
	v_mov_b32_e32 v62, v16
	v_mov_b32_e32 v63, v16
	s_branch .LBB0_511

; __global__ void __launch_bounds__(NTHR, 2) hymba_fwd(Params Pk) {
	.amdhsa_kernel _Z9hymba_fwd6Params
		.amdhsa_group_segment_fixed_size 0
		.amdhsa_private_segment_fixed_size 0
		.amdhsa_kernarg_size 560
		.amdhsa_user_sgpr_count 2
		.amdhsa_user_sgpr_dispatch_ptr 0
		.amdhsa_user_sgpr_queue_ptr 0
		.amdhsa_user_sgpr_kernarg_segment_ptr 1
		.amdhsa_user_sgpr_dispatch_id 0
		.amdhsa_user_sgpr_kernarg_preload_length 0
		.amdhsa_user_sgpr_kernarg_preload_offset 0
		.amdhsa_user_sgpr_private_segment_size 0
		.amdhsa_uses_dynamic_stack 0
		.amdhsa_enable_private_segment 0
		.amdhsa_system_sgpr_workgroup_id_x 1
		.amdhsa_system_sgpr_workgroup_id_y 0
		.amdhsa_system_sgpr_workgroup_id_z 0
		.amdhsa_system_sgpr_workgroup_info 0
		.amdhsa_system_vgpr_workitem_id 2
		.amdhsa_next_free_vgpr 250
		.amdhsa_next_free_sgpr 100
		.amdhsa_accum_offset 252
		.amdhsa_reserve_vcc 1
		.amdhsa_float_round_mode_32 0
		.amdhsa_float_round_mode_16_64 0
		.amdhsa_float_denorm_mode_32 3
		.amdhsa_float_denorm_mode_16_64 3
		.amdhsa_dx10_clamp 1
		.amdhsa_ieee_mode 1
		.amdhsa_fp16_overflow 0
		.amdhsa_tg_split 0
		.amdhsa_exception_fp_ieee_invalid_op 0
		.amdhsa_exception_fp_denorm_src 0
		.amdhsa_exception_fp_ieee_div_zero 0
		.amdhsa_exception_fp_ieee_overflow 0
		.amdhsa_exception_fp_ieee_underflow 0
		.amdhsa_exception_fp_ieee_inexact 0
		.amdhsa_exception_int_div_zero 0
	.end_amdhsa_kernel

; __global__ void __launch_bounds__(NTHR, 2) hymba_fwd(Params Pk) {
amdhsa.kernels:
  - .agpr_count:     0
    .args:
      - .offset:         0
        .size:           304
        .value_kind:     by_value
      - .offset:         304
        .size:           4
        .value_kind:     hidden_block_count_x
      - .offset:         308
        .size:           4
        .value_kind:     hidden_block_count_y
      - .offset:         312
        .size:           4
        .value_kind:     hidden_block_count_z
      - .offset:         316
        .size:           2
        .value_kind:     hidden_group_size_x
      - .offset:         318
        .size:           2
        .value_kind:     hidden_group_size_y
      - .offset:         320
        .size:           2
        .value_kind:     hidden_group_size_z
      - .offset:         322
        .size:           2
        .value_kind:     hidden_remainder_x
      - .offset:         324
        .size:           2
        .value_kind:     hidden_remainder_y
      - .offset:         326
        .size:           2
        .value_kind:     hidden_remainder_z
      - .offset:         344
        .size:           8
        .value_kind:     hidden_global_offset_x
      - .offset:         352
        .size:           8
        .value_kind:     hidden_global_offset_y
      - .offset:         360
        .size:           8
        .value_kind:     hidden_global_offset_z
      - .offset:         368
        .size:           2
        .value_kind:     hidden_grid_dims
      - .offset:         392
        .size:           8
        .value_kind:     hidden_multigrid_sync_arg
      - .offset:         424
        .size:           4
        .value_kind:     hidden_dynamic_lds_size
    .group_segment_fixed_size: 0
    .kernarg_segment_align: 8
    .kernarg_segment_size: 560
    .language:       OpenCL C
    .language_version:
      - 2
      - 0
    .max_flat_workgroup_size: 512
    .name:           _Z9hymba_fwd6Params
    .private_segment_fixed_size: 0
    .sgpr_count:     106
    .sgpr_spill_count: 152
    .symbol:         _Z9hymba_fwd6Params.kd
    .uniform_work_group_size: 1
    .uses_dynamic_stack: false
    .vgpr_count:     250
    .vgpr_spill_count: 0
    .wavefront_size: 64
